# no setprio flips + conv LN tail rewrite + K-loop heads aligned to 64 bytes
# speedup vs baseline: 1.0009x; 1.0009x over previous
;     __device__ bool next(int i, Unit& u) const { int pm, pn; if (!so.next(i, pm, pn)) return false; u.pm = pm; u.pn = pn; u.aoff = (unsigned)pm * BM * lda; u.boff = (unsigned)pn * BM * ldb; return true; }
;     __device__ __forceinline__ bool next(int i, Unit& u) const { int pm, pn; if (!so.next(i, pm, pn)) return false; u.pm = pm; u.pn = pn; u.aoff = (unsigned)pm * BM * lda; u.boff = (unsigned)(pm >> 4) * bstride + (unsigned)pn * BM * ldb; return true; }
;     __device__ __forceinline__ bool next(int i, Unit& u) const { int pm, pn; if (!so.next(i, pm, pn)) return false; u.pm = pm; u.pn = ((pn & 12) == 4 || (pn & 12) == 8) ? (pn ^ 12) : pn; u.aoff = (unsigned)pm * BM * lda; u.boff = (unsigned)pn * BM * ldb; return true; }
; template <class Epi, class Sched, bool ALIGN_EPI>
; __device__ __forceinline__ void gemm_phase(LAS unsigned char* lds, const Gemm g, const Sched& S, const Epi& E) {
;     ...
;         const bool has_next = S.next(ui + 1, nxt);
;         const char* nA = has_next ? (const char*)g.A + (size_t)nxt.aoff * 2 : cA; const char* nB = has_next ? (const char*)g.Bt + (size_t)nxt.boff * 2 : cB;
;     ...
;         for (int a = 0; a < 2; ++a)
; #pragma unroll
;             for (int b = 0; b < 2; ++b)
; #pragma unroll
;                 for (int m = 0; m < 4; ++m)
; #pragma unroll
;                     for (int n = 0; n < 2; ++n) acc[a][b][m][n] = (f32x4){0.f, 0.f, 0.f, 0.f};
.LBB0_241:
	s_lshl_b64 s[42:43], s[4:5], 1
	s_add_u32 s42, s79, s42
	s_addc_u32 s43, s80, s43
	s_and_b64 s[44:45], s[38:39], exec
	s_mov_b32 s41, s5
	s_cselect_b32 vcc_lo, s43, s67
	s_cselect_b32 vcc_hi, s42, s66
	s_lshl_b64 s[44:45], s[40:41], 1
	s_add_u32 s64, s62, s44
	s_addc_u32 s65, s63, s45
	s_and_b64 s[44:45], s[38:39], exec
	s_cselect_b32 s41, s65, s69
	s_cselect_b32 s87, s64, s68
	s_add_u32 s66, s66, 0x80080
	s_addc_u32 s67, s67, 0
	s_add_u32 s44, s68, 0x100
	v_mov_b32_e32 v0, 0
	s_addc_u32 s45, s69, 0
	s_mov_b32 s72, -2
	v_mov_b32_e32 v1, v0
	v_mov_b32_e32 v2, v0
	v_mov_b32_e32 v3, v0
	v_mov_b32_e32 v4, v0
	v_mov_b32_e32 v5, v0
	v_mov_b32_e32 v6, v0
	v_mov_b32_e32 v7, v0
	v_mov_b32_e32 v8, v0
	v_mov_b32_e32 v9, v0
	v_mov_b32_e32 v10, v0
	v_mov_b32_e32 v11, v0
	v_mov_b32_e32 v16, v0
	v_mov_b32_e32 v17, v0
	v_mov_b32_e32 v18, v0
	v_mov_b32_e32 v19, v0
	v_mov_b32_e32 v24, v0
	v_mov_b32_e32 v25, v0
	v_mov_b32_e32 v26, v0
	v_mov_b32_e32 v27, v0
	v_mov_b32_e32 v32, v0
	v_mov_b32_e32 v33, v0
	v_mov_b32_e32 v34, v0
	v_mov_b32_e32 v35, v0
	v_mov_b32_e32 v40, v0
	v_mov_b32_e32 v41, v0
	v_mov_b32_e32 v42, v0
	v_mov_b32_e32 v43, v0
	v_mov_b32_e32 v48, v0
	v_mov_b32_e32 v49, v0
	v_mov_b32_e32 v50, v0
	v_mov_b32_e32 v51, v0
	v_mov_b32_e32 v12, v0
	v_mov_b32_e32 v13, v0
	v_mov_b32_e32 v14, v0
	v_mov_b32_e32 v15, v0
	v_mov_b32_e32 v20, v0
	v_mov_b32_e32 v21, v0
	v_mov_b32_e32 v22, v0
	v_mov_b32_e32 v23, v0
	v_mov_b32_e32 v28, v0
	v_mov_b32_e32 v29, v0
	v_mov_b32_e32 v30, v0
	v_mov_b32_e32 v31, v0
	v_mov_b32_e32 v36, v0
	v_mov_b32_e32 v37, v0
	v_mov_b32_e32 v38, v0
	v_mov_b32_e32 v39, v0
	v_mov_b32_e32 v44, v0
	v_mov_b32_e32 v45, v0
	v_mov_b32_e32 v46, v0
	v_mov_b32_e32 v47, v0
	v_mov_b32_e32 v52, v0
	v_mov_b32_e32 v53, v0
	v_mov_b32_e32 v54, v0
	v_mov_b32_e32 v55, v0
	v_mov_b32_e32 v56, v0
	v_mov_b32_e32 v57, v0
	v_mov_b32_e32 v58, v0
	v_mov_b32_e32 v59, v0
	v_mov_b32_e32 v60, v0
	v_mov_b32_e32 v61, v0
	v_mov_b32_e32 v62, v0
	v_mov_b32_e32 v63, v0
	v_mov_b32_e32 v64, v0
	v_mov_b32_e32 v65, v0
	v_mov_b32_e32 v66, v0
	v_mov_b32_e32 v67, v0
	v_mov_b32_e32 v68, v0
	v_mov_b32_e32 v69, v0
	v_mov_b32_e32 v70, v0
	v_mov_b32_e32 v71, v0
	v_mov_b32_e32 v76, v0
	v_mov_b32_e32 v77, v0
	v_mov_b32_e32 v78, v0
	v_mov_b32_e32 v79, v0
	v_mov_b32_e32 v84, v0
	v_mov_b32_e32 v85, v0
	v_mov_b32_e32 v86, v0
	v_mov_b32_e32 v87, v0
	v_mov_b32_e32 v92, v0
	v_mov_b32_e32 v93, v0
	v_mov_b32_e32 v94, v0
	v_mov_b32_e32 v95, v0
	v_mov_b32_e32 v100, v0
	v_mov_b32_e32 v101, v0
	s_waitcnt lgkmcnt(0)
	v_mov_b32_e32 v102, v0
	v_mov_b32_e32 v103, v0
	v_mov_b32_e32 v108, v0
	v_mov_b32_e32 v109, v0
	v_mov_b32_e32 v110, v0
	v_mov_b32_e32 v111, v0
	v_mov_b32_e32 v116, v0
	v_mov_b32_e32 v117, v0
	v_mov_b32_e32 v118, v0
	v_mov_b32_e32 v119, v0
	v_mov_b32_e32 v72, v0
	v_mov_b32_e32 v73, v0
	v_mov_b32_e32 v74, v0
	v_mov_b32_e32 v75, v0
	v_mov_b32_e32 v80, v0
	v_mov_b32_e32 v81, v0
	v_mov_b32_e32 v82, v0
	v_mov_b32_e32 v83, v0
	v_mov_b32_e32 v88, v0
	v_mov_b32_e32 v89, v0
	v_mov_b32_e32 v90, v0
	v_mov_b32_e32 v91, v0
	v_mov_b32_e32 v96, v0
	v_mov_b32_e32 v97, v0
	v_mov_b32_e32 v98, v0
	v_mov_b32_e32 v99, v0
	v_mov_b32_e32 v104, v0
	v_mov_b32_e32 v105, v0
	v_mov_b32_e32 v106, v0
	v_mov_b32_e32 v107, v0
	v_mov_b32_e32 v112, v0
	v_mov_b32_e32 v113, v0
	v_mov_b32_e32 v114, v0
	v_mov_b32_e32 v115, v0
	v_mov_b32_e32 v120, v0
	v_mov_b32_e32 v121, v0
	v_mov_b32_e32 v122, v0
	v_mov_b32_e32 v123, v0
	v_mov_b32_e32 v124, v0
	v_mov_b32_e32 v125, v0
	v_mov_b32_e32 v126, v0
	v_mov_b32_e32 v127, v0
	.p2align 6

;     __device__ bool next(int i, Unit& u) const { int pm, pn; if (!so.next(i, pm, pn)) return false; u.pm = pm; u.pn = pn; u.aoff = (unsigned)pm * BM * lda; u.boff = (unsigned)pn * BM * ldb; return true; }
;     __device__ __forceinline__ bool next(int i, Unit& u) const { int pm, pn; if (!so.next(i, pm, pn)) return false; u.pm = pm; u.pn = pn; u.aoff = (unsigned)pm * BM * lda; u.boff = (unsigned)(pm >> 4) * bstride + (unsigned)pn * BM * ldb; return true; }
;     __device__ __forceinline__ bool next(int i, Unit& u) const { int pm, pn; if (!so.next(i, pm, pn)) return false; u.pm = pm; u.pn = ((pn & 12) == 4 || (pn & 12) == 8) ? (pn ^ 12) : pn; u.aoff = (unsigned)pm * BM * lda; u.boff = (unsigned)pn * BM * ldb; return true; }
; template <class Epi, class Sched, bool ALIGN_EPI>
; __device__ __forceinline__ void gemm_phase(LAS unsigned char* lds, const Gemm g, const Sched& S, const Epi& E) {
;     ...
;         const bool has_next = S.next(ui + 1, nxt);
;         const char* nA = has_next ? (const char*)g.A + (size_t)nxt.aoff * 2 : cA; const char* nB = has_next ? (const char*)g.Bt + (size_t)nxt.boff * 2 : cB;
;     ...
;         for (int a = 0; a < 2; ++a)
; #pragma unroll
;             for (int b = 0; b < 2; ++b)
; #pragma unroll
;                 for (int m = 0; m < 4; ++m)
; #pragma unroll
;                     for (int n = 0; n < 2; ++n) acc[a][b][m][n] = (f32x4){0.f, 0.f, 0.f, 0.f};
.LBB0_260:
	s_lshl_b64 s[44:45], s[24:25], 1
	s_add_u32 s62, s50, s44
	s_addc_u32 s63, s51, s45
	s_and_b64 s[44:45], s[2:3], exec
	s_mov_b32 s43, s25
	s_cselect_b32 s93, s63, s5
	s_cselect_b32 s94, s62, s4
	s_lshl_b64 s[44:45], s[42:43], 1
	s_add_u32 s64, s14, s44
	s_addc_u32 s65, s15, s45
	s_and_b64 s[44:45], s[2:3], exec
	s_cselect_b32 s43, s65, s7
	s_cselect_b32 s87, s64, s6
	s_add_u32 s4, s4, 0x80080
	s_addc_u32 s5, s5, 0
	s_add_u32 s44, s6, 0x100
	v_mov_b32_e32 v0, 0
	s_addc_u32 s45, s7, 0
	s_mov_b32 s72, -2
	v_mov_b32_e32 v1, v0
	v_mov_b32_e32 v2, v0
	v_mov_b32_e32 v3, v0
	v_mov_b32_e32 v8, v0
	v_mov_b32_e32 v9, v0
	v_mov_b32_e32 v10, v0
	v_mov_b32_e32 v11, v0
	v_mov_b32_e32 v16, v0
	v_mov_b32_e32 v17, v0
	v_mov_b32_e32 v18, v0
	v_mov_b32_e32 v19, v0
	v_mov_b32_e32 v24, v0
	v_mov_b32_e32 v25, v0
	v_mov_b32_e32 v26, v0
	v_mov_b32_e32 v27, v0
	v_mov_b32_e32 v32, v0
	v_mov_b32_e32 v33, v0
	v_mov_b32_e32 v34, v0
	v_mov_b32_e32 v35, v0
	v_mov_b32_e32 v40, v0
	v_mov_b32_e32 v41, v0
	v_mov_b32_e32 v42, v0
	v_mov_b32_e32 v43, v0
	v_mov_b32_e32 v48, v0
	v_mov_b32_e32 v49, v0
	v_mov_b32_e32 v50, v0
	v_mov_b32_e32 v51, v0
	v_mov_b32_e32 v56, v0
	v_mov_b32_e32 v57, v0
	v_mov_b32_e32 v58, v0
	v_mov_b32_e32 v59, v0
	v_mov_b32_e32 v4, v0
	v_mov_b32_e32 v5, v0
	v_mov_b32_e32 v6, v0
	v_mov_b32_e32 v7, v0
	v_mov_b32_e32 v12, v0
	v_mov_b32_e32 v13, v0
	v_mov_b32_e32 v14, v0
	v_mov_b32_e32 v15, v0
	v_mov_b32_e32 v20, v0
	v_mov_b32_e32 v21, v0
	v_mov_b32_e32 v22, v0
	v_mov_b32_e32 v23, v0
	v_mov_b32_e32 v28, v0
	v_mov_b32_e32 v29, v0
	v_mov_b32_e32 v30, v0
	v_mov_b32_e32 v31, v0
	v_mov_b32_e32 v36, v0
	v_mov_b32_e32 v37, v0
	v_mov_b32_e32 v38, v0
	v_mov_b32_e32 v39, v0
	v_mov_b32_e32 v44, v0
	v_mov_b32_e32 v45, v0
	v_mov_b32_e32 v46, v0
	v_mov_b32_e32 v47, v0
	v_mov_b32_e32 v52, v0
	v_mov_b32_e32 v53, v0
	v_mov_b32_e32 v54, v0
	v_mov_b32_e32 v55, v0
	v_mov_b32_e32 v60, v0
	v_mov_b32_e32 v61, v0
	v_mov_b32_e32 v62, v0
	v_mov_b32_e32 v63, v0
	v_mov_b32_e32 v64, v0
	v_mov_b32_e32 v65, v0
	v_mov_b32_e32 v66, v0
	v_mov_b32_e32 v67, v0
	v_mov_b32_e32 v72, v0
	v_mov_b32_e32 v73, v0
	v_mov_b32_e32 v74, v0
	v_mov_b32_e32 v75, v0
	v_mov_b32_e32 v80, v0
	v_mov_b32_e32 v81, v0
	v_mov_b32_e32 v82, v0
	v_mov_b32_e32 v83, v0
	v_mov_b32_e32 v88, v0
	v_mov_b32_e32 v89, v0
	v_mov_b32_e32 v90, v0
	v_mov_b32_e32 v91, v0
	v_mov_b32_e32 v96, v0
	s_waitcnt lgkmcnt(0)
	v_mov_b32_e32 v97, v0
	v_mov_b32_e32 v98, v0
	v_mov_b32_e32 v99, v0
	v_mov_b32_e32 v104, v0
	v_mov_b32_e32 v105, v0
	v_mov_b32_e32 v106, v0
	v_mov_b32_e32 v107, v0
	v_mov_b32_e32 v112, v0
	v_mov_b32_e32 v113, v0
	v_mov_b32_e32 v114, v0
	v_mov_b32_e32 v115, v0
	v_mov_b32_e32 v120, v0
	v_mov_b32_e32 v121, v0
	v_mov_b32_e32 v122, v0
	v_mov_b32_e32 v123, v0
	v_mov_b32_e32 v68, v0
	v_mov_b32_e32 v69, v0
	v_mov_b32_e32 v70, v0
	v_mov_b32_e32 v71, v0
	v_mov_b32_e32 v76, v0
	v_mov_b32_e32 v77, v0
	v_mov_b32_e32 v78, v0
	v_mov_b32_e32 v79, v0
	v_mov_b32_e32 v84, v0
	v_mov_b32_e32 v85, v0
	v_mov_b32_e32 v86, v0
	v_mov_b32_e32 v87, v0
	v_mov_b32_e32 v92, v0
	v_mov_b32_e32 v93, v0
	v_mov_b32_e32 v94, v0
	v_mov_b32_e32 v95, v0
	v_mov_b32_e32 v100, v0
	v_mov_b32_e32 v101, v0
	v_mov_b32_e32 v102, v0
	v_mov_b32_e32 v103, v0
	v_mov_b32_e32 v108, v0
	v_mov_b32_e32 v109, v0
	v_mov_b32_e32 v110, v0
	v_mov_b32_e32 v111, v0
	v_mov_b32_e32 v116, v0
	v_mov_b32_e32 v117, v0
	v_mov_b32_e32 v118, v0
	v_mov_b32_e32 v119, v0
	v_mov_b32_e32 v124, v0
	v_mov_b32_e32 v125, v0
	v_mov_b32_e32 v126, v0
	v_mov_b32_e32 v127, v0
	.p2align 6

; #define PG8_STAGE(bufoff, gbase, voff) do { _Pragma("unroll") for (int _i = 0; _i < 2; ++_i) \
;         __builtin_amdgcn_global_load_lds((const unsigned*)((const char*)(gbase) + (voff)[_i]), (LAS unsigned*)(lds + (bufoff) + ldsw + _i * 8192), 16, 0, 0); } while (0)
; #define PG8_WAIT_V(n) asm volatile("s_waitcnt vmcnt(" #n ")" ::: "memory")
; #define PG8_BAR __builtin_amdgcn_s_barrier()
; template <class Epi, class Sched, bool ALIGN_EPI>
; __device__ __forceinline__ void gemm_phase(LAS unsigned char* lds, const Gemm g, const Sched& S, const Epi& E) {
;     ...
;     f32x4 acc[2][2][4][2];
; #pragma unroll
;     for (int a = 0; a < 2; ++a)
; #pragma unroll
;         for (int b = 0; b < 2; ++b)
; #pragma unroll
;             for (int m = 0; m < 4; ++m)
; #pragma unroll
;                 for (int n = 0; n < 2; ++n) acc[a][b][m][n] = (f32x4){0.f, 0.f, 0.f, 0.f};
;     ...
;     const char* cA = (const char*)g.A + (size_t)cur.aoff * 2; const char* cB = (const char*)g.Bt + (size_t)cur.boff * 2;
;     PG8_STAGE(PG8_SB(0, 0), cB, voffB); PG8_STAGE(PG8_SB(0, 1), cB + hB, voffB); PG8_STAGE(PG8_SA(0, 0), cA, voffA); PG8_STAGE(PG8_SA(0, 1), cA + hA, voffA);
;     if (wr == 1) PG8_BAR;
;     PG8_WAIT_V(2); PG8_BAR;
;     PG8_STAGE(PG8_SB(1, 0), cB + kstep, voffB); PG8_STAGE(PG8_SA(1, 0), cA + kstep, voffA); PG8_STAGE(PG8_SB(1, 1), cB + hB + kstep, voffB);
;     PG8_WAIT_V(6); PG8_BAR;
.LBB0_278:
	s_lshl_b32 s6, s42, 5
	s_add_i32 m0, s27, 0x18000
	v_lshl_add_u64 v[0:1], v[0:1], 0, s[24:25]
	s_and_b32 s74, s6, 0x60
	s_waitcnt vmcnt(2)
	s_barrier
	global_load_lds_dwordx4 v[0:1], off
	v_lshl_add_u64 v[0:1], v[2:3], 0, s[24:25]
	s_add_i32 m0, s27, 0x1a000
	s_add_i32 s78, s27, 0x8000
	s_add_i32 s79, s27, 0xa000
	global_load_lds_dwordx4 v[0:1], off
	v_lshl_add_u64 v[0:1], v[6:7], 0, s[24:25]
	s_mov_b32 m0, s78
	s_add_u32 s42, s36, 0x80080
	global_load_lds_dwordx4 v[0:1], off
	v_lshl_add_u64 v[0:1], v[4:5], 0, s[24:25]
	s_mov_b32 m0, s79
	s_addc_u32 s43, s37, 0
	global_load_lds_dwordx4 v[0:1], off
	s_add_i32 m0, s27, 0x1c000
	v_lshl_add_u64 v[0:1], s[42:43], 0, v[144:145]
	global_load_lds_dwordx4 v[0:1], off
	v_lshl_add_u64 v[0:1], s[42:43], 0, v[146:147]
	s_add_i32 m0, s27, 0x1e000
	v_mov_b32_e32 v127, 0
	global_load_lds_dwordx4 v[0:1], off
	s_waitcnt vmcnt(6)
	v_lshl_or_b32 v132, s41, 6, v182
	s_and_b64 vcc, exec, s[4:5]
	v_mov_b32_e32 v126, v127
	v_mov_b32_e32 v125, v127
	v_mov_b32_e32 v124, v127
	v_mov_b32_e32 v123, v127
	v_mov_b32_e32 v122, v127
	v_mov_b32_e32 v121, v127
	v_mov_b32_e32 v120, v127
	v_mov_b32_e32 v111, v127
	v_mov_b32_e32 v110, v127
	v_mov_b32_e32 v109, v127
	v_mov_b32_e32 v108, v127
	v_mov_b32_e32 v107, v127
	v_mov_b32_e32 v106, v127
	v_mov_b32_e32 v105, v127
	v_mov_b32_e32 v104, v127
	v_mov_b32_e32 v95, v127
	v_mov_b32_e32 v94, v127
	v_mov_b32_e32 v93, v127
	v_mov_b32_e32 v92, v127
	v_mov_b32_e32 v91, v127
	v_mov_b32_e32 v90, v127
	v_mov_b32_e32 v89, v127
	v_mov_b32_e32 v88, v127
	v_mov_b32_e32 v79, v127
	v_mov_b32_e32 v78, v127
	v_mov_b32_e32 v77, v127
	v_mov_b32_e32 v76, v127
	v_mov_b32_e32 v75, v127
	v_mov_b32_e32 v74, v127
	v_mov_b32_e32 v73, v127
	v_mov_b32_e32 v72, v127
	v_mov_b32_e32 v119, v127
	v_mov_b32_e32 v118, v127
	v_mov_b32_e32 v117, v127
	v_mov_b32_e32 v116, v127
	v_mov_b32_e32 v115, v127
	v_mov_b32_e32 v114, v127
	v_mov_b32_e32 v113, v127
	v_mov_b32_e32 v112, v127
	v_mov_b32_e32 v103, v127
	v_mov_b32_e32 v102, v127
	v_mov_b32_e32 v101, v127
	v_mov_b32_e32 v100, v127
	v_mov_b32_e32 v99, v127
	v_mov_b32_e32 v98, v127
	v_mov_b32_e32 v97, v127
	v_mov_b32_e32 v96, v127
	v_mov_b32_e32 v87, v127
	v_mov_b32_e32 v86, v127
	v_mov_b32_e32 v85, v127
	v_mov_b32_e32 v84, v127
	v_mov_b32_e32 v83, v127
	v_mov_b32_e32 v82, v127
	v_mov_b32_e32 v81, v127
	v_mov_b32_e32 v80, v127
	v_mov_b32_e32 v71, v127
	v_mov_b32_e32 v70, v127
	v_mov_b32_e32 v69, v127
	v_mov_b32_e32 v68, v127
	v_mov_b32_e32 v67, v127
	v_mov_b32_e32 v66, v127
	v_mov_b32_e32 v65, v127
	v_mov_b32_e32 v64, v127
	v_mov_b32_e32 v63, v127
	v_mov_b32_e32 v62, v127
	v_mov_b32_e32 v61, v127
	v_mov_b32_e32 v60, v127
	v_mov_b32_e32 v59, v127
	v_mov_b32_e32 v58, v127
	v_mov_b32_e32 v57, v127
	v_mov_b32_e32 v56, v127
	v_mov_b32_e32 v47, v127
	v_mov_b32_e32 v46, v127
	v_mov_b32_e32 v45, v127
	v_mov_b32_e32 v44, v127
	v_mov_b32_e32 v43, v127
	v_mov_b32_e32 v42, v127
	v_mov_b32_e32 v41, v127
	v_mov_b32_e32 v40, v127
	v_mov_b32_e32 v31, v127
	v_mov_b32_e32 v30, v127
	v_mov_b32_e32 v29, v127
	v_mov_b32_e32 v28, v127
	v_mov_b32_e32 v27, v127
	v_mov_b32_e32 v26, v127
	v_mov_b32_e32 v25, v127
	v_mov_b32_e32 v24, v127
	v_mov_b32_e32 v15, v127
	v_mov_b32_e32 v14, v127
	v_mov_b32_e32 v13, v127
	v_mov_b32_e32 v12, v127
	v_mov_b32_e32 v11, v127
	v_mov_b32_e32 v10, v127
	v_mov_b32_e32 v9, v127
	v_mov_b32_e32 v8, v127
	v_mov_b32_e32 v55, v127
	v_mov_b32_e32 v54, v127
	v_mov_b32_e32 v53, v127
	v_mov_b32_e32 v52, v127
	v_mov_b32_e32 v51, v127
	v_mov_b32_e32 v50, v127
	v_mov_b32_e32 v49, v127
	v_mov_b32_e32 v48, v127
	v_mov_b32_e32 v39, v127
	v_mov_b32_e32 v38, v127
	v_mov_b32_e32 v37, v127
	v_mov_b32_e32 v36, v127
	v_mov_b32_e32 v35, v127
	v_mov_b32_e32 v34, v127
	v_mov_b32_e32 v33, v127
	v_mov_b32_e32 v32, v127
	v_mov_b32_e32 v23, v127
	v_mov_b32_e32 v22, v127
	v_mov_b32_e32 v21, v127
	v_mov_b32_e32 v20, v127
	v_mov_b32_e32 v19, v127
	v_mov_b32_e32 v18, v127
	v_mov_b32_e32 v17, v127
	v_mov_b32_e32 v16, v127
	v_mov_b32_e32 v7, v127
	v_mov_b32_e32 v6, v127
	v_mov_b32_e32 v5, v127
	v_mov_b32_e32 v4, v127
	v_mov_b32_e32 v3, v127
	v_mov_b32_e32 v2, v127
	v_mov_b32_e32 v1, v127
	v_mov_b32_e32 v0, v127
	s_barrier
; template <class Epi, class Sched, bool ALIGN_EPI>
; __device__ __forceinline__ void gemm_phase(LAS unsigned char* lds, const Gemm g, const Sched& S, const Epi& E) {
;     ...
;     for (int i = 0; i < 2; ++i) { int R, C; stage_rc(tid * 16 + i * 8192, R, C); const int Rb = Epi::PERM ? ((R & ~31) + perm32(R & 31)) : R;
;         voffA[i] = (unsigned)(R * g.lda + C) * 2u; voffB[i] = (unsigned)(Rb * g.ldb + C) * 2u; }
;     const size_t kstep = (size_t)(BK * 2);
;     const size_t hA = (size_t)HALF * g.lda * 2, hB = (size_t)HALF * g.ldb * 2;
;     const unsigned ldsw = (unsigned)wid * 1024u;
;     const int aoff = lds_byte(wr * 64 + fr, fq * 8), boff = lds_byte(wc * 32 + fr, fq * 8);
;     ...
;     f32x4 acc[2][2][4][2];
; #pragma unroll
;     for (int a = 0; a < 2; ++a)
; #pragma unroll
;         for (int b = 0; b < 2; ++b)
; #pragma unroll
;             for (int m = 0; m < 4; ++m)
; #pragma unroll
;                 for (int n = 0; n < 2; ++n) acc[a][b][m][n] = (f32x4){0.f, 0.f, 0.f, 0.f};
	s_cbranch_vccnz .LBB0_281
	s_lshr_b32 s6, s64, 3
	s_and_b32 s6, s6, 3
	v_lshlrev_b32_e32 v0, 6, v132
	v_lshlrev_b32_e32 v1, 2, v132
	s_lshl_b32 s6, s6, 9
	v_and_or_b32 v0, v0, s67, v183
	v_and_b32_e32 v1, 32, v1
	s_lshl_b32 s18, s41, 13
	s_add_i32 s6, s40, s6
	v_lshl_or_b32 v142, s74, 7, v184
	v_bitop3_b32 v1, v0, s18, v1 bitop3:0xde
	s_lshl_b64 s[40:41], s[6:7], 1
	v_mov_b32_e32 v0, 0
	s_add_i32 s45, s68, s11
	s_add_i32 s47, s69, s11
	v_lshl_add_u64 v[138:139], v[134:135], 0, s[40:41]
	v_lshl_add_u64 v[140:141], v[136:137], 0, s[40:41]
	s_mov_b32 s42, 0
	s_mov_b64 s[40:41], 0xc000080
	v_add_u32_e32 v143, 0, v1
	v_add_u32_e32 v148, s68, v142
	v_add_u32_e32 v149, s69, v142
	s_add_i32 s6, s27, 0xc000
	s_add_i32 s44, s27, 0xe000
	s_add_i32 s46, s45, 0x2000
	s_add_i32 s72, s47, 0x2000
	v_mov_b32_e32 v1, v0
	v_mov_b32_e32 v2, v0
	v_mov_b32_e32 v3, v0
	v_mov_b32_e32 v4, v0
	v_mov_b32_e32 v5, v0
	v_mov_b32_e32 v6, v0
	v_mov_b32_e32 v7, v0
	v_mov_b32_e32 v16, v0
	v_mov_b32_e32 v17, v0
	v_mov_b32_e32 v18, v0
	v_mov_b32_e32 v19, v0
	v_mov_b32_e32 v20, v0
	v_mov_b32_e32 v21, v0
	v_mov_b32_e32 v22, v0
	v_mov_b32_e32 v23, v0
	v_mov_b32_e32 v32, v0
	v_mov_b32_e32 v33, v0
	v_mov_b32_e32 v34, v0
	v_mov_b32_e32 v35, v0
	v_mov_b32_e32 v36, v0
	v_mov_b32_e32 v37, v0
	v_mov_b32_e32 v38, v0
	v_mov_b32_e32 v39, v0
	v_mov_b32_e32 v48, v0
	v_mov_b32_e32 v49, v0
	v_mov_b32_e32 v50, v0
	v_mov_b32_e32 v51, v0
	v_mov_b32_e32 v52, v0
	v_mov_b32_e32 v53, v0
	v_mov_b32_e32 v54, v0
	v_mov_b32_e32 v55, v0
	v_mov_b32_e32 v8, v0
	v_mov_b32_e32 v9, v0
	v_mov_b32_e32 v10, v0
	v_mov_b32_e32 v11, v0
	v_mov_b32_e32 v12, v0
	v_mov_b32_e32 v13, v0
	v_mov_b32_e32 v14, v0
	v_mov_b32_e32 v15, v0
	v_mov_b32_e32 v24, v0
	v_mov_b32_e32 v25, v0
	v_mov_b32_e32 v26, v0
	v_mov_b32_e32 v27, v0
	v_mov_b32_e32 v28, v0
	v_mov_b32_e32 v29, v0
	v_mov_b32_e32 v30, v0
	v_mov_b32_e32 v31, v0
	v_mov_b32_e32 v40, v0
	v_mov_b32_e32 v41, v0
	v_mov_b32_e32 v42, v0
	v_mov_b32_e32 v43, v0
	v_mov_b32_e32 v44, v0
	v_mov_b32_e32 v45, v0
	v_mov_b32_e32 v46, v0
	v_mov_b32_e32 v47, v0
	v_mov_b32_e32 v56, v0
	v_mov_b32_e32 v57, v0
	v_mov_b32_e32 v58, v0
	v_mov_b32_e32 v59, v0
	v_mov_b32_e32 v60, v0
	v_mov_b32_e32 v61, v0
	v_mov_b32_e32 v62, v0
	v_mov_b32_e32 v63, v0
	v_mov_b32_e32 v64, v0
	v_mov_b32_e32 v65, v0
	v_mov_b32_e32 v66, v0
	v_mov_b32_e32 v67, v0
	v_mov_b32_e32 v68, v0
	v_mov_b32_e32 v69, v0
	v_mov_b32_e32 v70, v0
	v_mov_b32_e32 v71, v0
	v_mov_b32_e32 v80, v0
	v_mov_b32_e32 v81, v0
	v_mov_b32_e32 v82, v0
	v_mov_b32_e32 v83, v0
	v_mov_b32_e32 v84, v0
	v_mov_b32_e32 v85, v0
	v_mov_b32_e32 v86, v0
	v_mov_b32_e32 v87, v0
	v_mov_b32_e32 v96, v0
	v_mov_b32_e32 v97, v0
	v_mov_b32_e32 v98, v0
	v_mov_b32_e32 v99, v0
	v_mov_b32_e32 v100, v0
	v_mov_b32_e32 v101, v0
	v_mov_b32_e32 v102, v0
	v_mov_b32_e32 v103, v0
	v_mov_b32_e32 v112, v0
	v_mov_b32_e32 v113, v0
	v_mov_b32_e32 v114, v0
	v_mov_b32_e32 v115, v0
	v_mov_b32_e32 v116, v0
	v_mov_b32_e32 v117, v0
	v_mov_b32_e32 v118, v0
	v_mov_b32_e32 v119, v0
	v_mov_b32_e32 v72, v0
	v_mov_b32_e32 v73, v0
	v_mov_b32_e32 v74, v0
	v_mov_b32_e32 v75, v0
	v_mov_b32_e32 v76, v0
	v_mov_b32_e32 v77, v0
	v_mov_b32_e32 v78, v0
	v_mov_b32_e32 v79, v0
	v_mov_b32_e32 v88, v0
	v_mov_b32_e32 v89, v0
	v_mov_b32_e32 v90, v0
	v_mov_b32_e32 v91, v0
	v_mov_b32_e32 v92, v0
	v_mov_b32_e32 v93, v0
	v_mov_b32_e32 v94, v0
	v_mov_b32_e32 v95, v0
	v_mov_b32_e32 v104, v0
	v_mov_b32_e32 v105, v0
	v_mov_b32_e32 v106, v0
	v_mov_b32_e32 v107, v0
	v_mov_b32_e32 v108, v0
	v_mov_b32_e32 v109, v0
	v_mov_b32_e32 v110, v0
	v_mov_b32_e32 v111, v0
	v_mov_b32_e32 v120, v0
	v_mov_b32_e32 v121, v0
	v_mov_b32_e32 v122, v0
	v_mov_b32_e32 v123, v0
	v_mov_b32_e32 v124, v0
	v_mov_b32_e32 v125, v0
	v_mov_b32_e32 v126, v0
	v_mov_b32_e32 v127, v0
	.p2align 6

;     __device__ bool next(int i, Unit& u) const { int pm, pn; if (!so.next(i, pm, pn)) return false; u.pm = pm; u.pn = pn; u.aoff = (unsigned)pm * BM * lda; u.boff = (unsigned)pn * BM * ldb; return true; }
;     __device__ __forceinline__ bool next(int i, Unit& u) const { int pm, pn; if (!so.next(i, pm, pn)) return false; u.pm = pm; u.pn = pn; u.aoff = (unsigned)pm * BM * lda; u.boff = (unsigned)(pm >> 4) * bstride + (unsigned)pn * BM * ldb; return true; }
;     __device__ __forceinline__ bool next(int i, Unit& u) const { int pm, pn; if (!so.next(i, pm, pn)) return false; u.pm = pm; u.pn = ((pn & 12) == 4 || (pn & 12) == 8) ? (pn ^ 12) : pn; u.aoff = (unsigned)pm * BM * lda; u.boff = (unsigned)pn * BM * ldb; return true; }
; template <class Epi, class Sched, bool ALIGN_EPI>
; __device__ __forceinline__ void gemm_phase(LAS unsigned char* lds, const Gemm g, const Sched& S, const Epi& E) {
;     ...
;         const bool has_next = S.next(ui + 1, nxt);
;         const char* nA = has_next ? (const char*)g.A + (size_t)nxt.aoff * 2 : cA; const char* nB = has_next ? (const char*)g.Bt + (size_t)nxt.boff * 2 : cB;
;     ...
;         for (int a = 0; a < 2; ++a)
; #pragma unroll
;             for (int b = 0; b < 2; ++b)
; #pragma unroll
;                 for (int m = 0; m < 4; ++m)
; #pragma unroll
;                     for (int n = 0; n < 2; ++n) acc[a][b][m][n] = (f32x4){0.f, 0.f, 0.f, 0.f};
.LBB0_360:
	s_lshl_b64 s[38:39], s[20:21], 1
	s_add_u32 s38, s28, s38
	s_addc_u32 s39, s29, s39
	s_and_b64 s[40:41], s[4:5], exec
	s_mov_b32 s37, s21
	s_cselect_b32 s81, s39, s43
	s_cselect_b32 s82, s38, s42
	s_lshl_b64 s[40:41], s[36:37], 1
	s_add_u32 s40, s58, s40
	s_addc_u32 s41, s59, s41
	s_and_b64 s[44:45], s[4:5], exec
	s_cselect_b32 s37, s41, s61
	s_cselect_b32 s83, s40, s60
	s_add_u32 s42, s42, 0x160080
	s_addc_u32 s43, s43, 0
	s_add_u32 s44, s60, 0x100
	v_mov_b32_e32 v0, 0
	s_addc_u32 s45, s61, 0
	s_mov_b32 s84, -2
	s_waitcnt lgkmcnt(0)
	v_mov_b32_e32 v1, v0
	v_mov_b32_e32 v2, v0
	v_mov_b32_e32 v3, v0
	v_mov_b32_e32 v4, v0
	v_mov_b32_e32 v5, v0
	v_mov_b32_e32 v6, v0
	v_mov_b32_e32 v7, v0
	v_mov_b32_e32 v16, v0
	v_mov_b32_e32 v17, v0
	v_mov_b32_e32 v18, v0
	v_mov_b32_e32 v19, v0
	v_mov_b32_e32 v20, v0
	v_mov_b32_e32 v21, v0
	v_mov_b32_e32 v22, v0
	v_mov_b32_e32 v23, v0
	v_mov_b32_e32 v32, v0
	v_mov_b32_e32 v33, v0
	v_mov_b32_e32 v34, v0
	v_mov_b32_e32 v35, v0
	v_mov_b32_e32 v36, v0
	v_mov_b32_e32 v37, v0
	v_mov_b32_e32 v38, v0
	v_mov_b32_e32 v39, v0
	v_mov_b32_e32 v48, v0
	v_mov_b32_e32 v49, v0
	v_mov_b32_e32 v50, v0
	v_mov_b32_e32 v51, v0
	v_mov_b32_e32 v52, v0
	v_mov_b32_e32 v53, v0
	v_mov_b32_e32 v54, v0
	v_mov_b32_e32 v55, v0
	v_mov_b32_e32 v8, v0
	v_mov_b32_e32 v9, v0
	v_mov_b32_e32 v10, v0
	v_mov_b32_e32 v11, v0
	v_mov_b32_e32 v12, v0
	v_mov_b32_e32 v13, v0
	v_mov_b32_e32 v14, v0
	v_mov_b32_e32 v15, v0
	v_mov_b32_e32 v24, v0
	v_mov_b32_e32 v25, v0
	v_mov_b32_e32 v26, v0
	v_mov_b32_e32 v27, v0
	v_mov_b32_e32 v28, v0
	v_mov_b32_e32 v29, v0
	v_mov_b32_e32 v30, v0
	v_mov_b32_e32 v31, v0
	v_mov_b32_e32 v40, v0
	v_mov_b32_e32 v41, v0
	v_mov_b32_e32 v42, v0
	v_mov_b32_e32 v43, v0
	v_mov_b32_e32 v44, v0
	v_mov_b32_e32 v45, v0
	v_mov_b32_e32 v46, v0
	v_mov_b32_e32 v47, v0
	v_mov_b32_e32 v56, v0
	v_mov_b32_e32 v57, v0
	v_mov_b32_e32 v58, v0
	v_mov_b32_e32 v59, v0
	v_mov_b32_e32 v60, v0
	v_mov_b32_e32 v61, v0
	v_mov_b32_e32 v62, v0
	v_mov_b32_e32 v63, v0
	v_mov_b32_e32 v64, v0
	v_mov_b32_e32 v65, v0
	v_mov_b32_e32 v66, v0
	v_mov_b32_e32 v67, v0
	v_mov_b32_e32 v68, v0
	v_mov_b32_e32 v69, v0
	v_mov_b32_e32 v70, v0
	v_mov_b32_e32 v71, v0
	v_mov_b32_e32 v80, v0
	v_mov_b32_e32 v81, v0
	v_mov_b32_e32 v82, v0
	v_mov_b32_e32 v83, v0
	v_mov_b32_e32 v84, v0
	v_mov_b32_e32 v85, v0
	v_mov_b32_e32 v86, v0
	v_mov_b32_e32 v87, v0
	v_mov_b32_e32 v96, v0
	s_waitcnt lgkmcnt(0)
	v_mov_b32_e32 v97, v0
	v_mov_b32_e32 v98, v0
	v_mov_b32_e32 v99, v0
	v_mov_b32_e32 v100, v0
	v_mov_b32_e32 v101, v0
	v_mov_b32_e32 v102, v0
	v_mov_b32_e32 v103, v0
	v_mov_b32_e32 v112, v0
	v_mov_b32_e32 v113, v0
	v_mov_b32_e32 v114, v0
	v_mov_b32_e32 v115, v0
	v_mov_b32_e32 v116, v0
	v_mov_b32_e32 v117, v0
	v_mov_b32_e32 v118, v0
	v_mov_b32_e32 v119, v0
	v_mov_b32_e32 v72, v0
	v_mov_b32_e32 v73, v0
	v_mov_b32_e32 v74, v0
	v_mov_b32_e32 v75, v0
	v_mov_b32_e32 v76, v0
	v_mov_b32_e32 v77, v0
	v_mov_b32_e32 v78, v0
	v_mov_b32_e32 v79, v0
	v_mov_b32_e32 v88, v0
	v_mov_b32_e32 v89, v0
	v_mov_b32_e32 v90, v0
	v_mov_b32_e32 v91, v0
	v_mov_b32_e32 v92, v0
	v_mov_b32_e32 v93, v0
	v_mov_b32_e32 v94, v0
	v_mov_b32_e32 v95, v0
	v_mov_b32_e32 v104, v0
	v_mov_b32_e32 v105, v0
	v_mov_b32_e32 v106, v0
	v_mov_b32_e32 v107, v0
	v_mov_b32_e32 v108, v0
	v_mov_b32_e32 v109, v0
	v_mov_b32_e32 v110, v0
	v_mov_b32_e32 v111, v0
	v_mov_b32_e32 v120, v0
	v_mov_b32_e32 v121, v0
	v_mov_b32_e32 v122, v0
	v_mov_b32_e32 v123, v0
	v_mov_b32_e32 v124, v0
	v_mov_b32_e32 v125, v0
	v_mov_b32_e32 v126, v0
	v_mov_b32_e32 v127, v0
	.p2align 6

;     __device__ bool next(int i, Unit& u) const { int pm, pn; if (!so.next(i, pm, pn)) return false; u.pm = pm; u.pn = pn; u.aoff = (unsigned)pm * BM * lda; u.boff = (unsigned)pn * BM * ldb; return true; }
;     __device__ __forceinline__ bool next(int i, Unit& u) const { int pm, pn; if (!so.next(i, pm, pn)) return false; u.pm = pm; u.pn = pn; u.aoff = (unsigned)pm * BM * lda; u.boff = (unsigned)(pm >> 4) * bstride + (unsigned)pn * BM * ldb; return true; }
;     __device__ __forceinline__ bool next(int i, Unit& u) const { int pm, pn; if (!so.next(i, pm, pn)) return false; u.pm = pm; u.pn = ((pn & 12) == 4 || (pn & 12) == 8) ? (pn ^ 12) : pn; u.aoff = (unsigned)pm * BM * lda; u.boff = (unsigned)pn * BM * ldb; return true; }
; template <class Epi, class Sched, bool ALIGN_EPI>
; __device__ __forceinline__ void gemm_phase(LAS unsigned char* lds, const Gemm g, const Sched& S, const Epi& E) {
;     ...
;         const bool has_next = S.next(ui + 1, nxt);
;         const char* nA = has_next ? (const char*)g.A + (size_t)nxt.aoff * 2 : cA; const char* nB = has_next ? (const char*)g.Bt + (size_t)nxt.boff * 2 : cB;
;     ...
;         for (int a = 0; a < 2; ++a)
; #pragma unroll
;             for (int b = 0; b < 2; ++b)
; #pragma unroll
;                 for (int m = 0; m < 4; ++m)
; #pragma unroll
;                     for (int n = 0; n < 2; ++n) acc[a][b][m][n] = (f32x4){0.f, 0.f, 0.f, 0.f};
.LBB0_465:
	s_lshl_b64 s[44:45], s[22:23], 1
	s_add_u32 s76, s50, s44
	s_addc_u32 s77, s51, s45
	s_and_b64 s[44:45], s[4:5], exec
	s_mov_b32 s75, s23
	s_cselect_b32 vcc_lo, s77, s7
	s_cselect_b32 vcc_hi, s76, s6
	s_lshl_b64 s[44:45], s[74:75], 1
	s_add_u32 s78, s56, s44
	s_addc_u32 s79, s57, s45
	s_and_b64 s[44:45], s[4:5], exec
	s_cselect_b32 s75, s79, s81
	s_cselect_b32 s87, s78, s80
	s_add_u32 s6, s6, 0x80080
	s_addc_u32 s7, s7, 0
	s_add_u32 s44, s80, 0x100
	v_mov_b32_e32 v0, 0
	s_addc_u32 s45, s81, 0
	s_mov_b32 s46, -2
	v_mov_b32_e32 v1, v0
	v_mov_b32_e32 v2, v0
	v_mov_b32_e32 v3, v0
	v_mov_b32_e32 v8, v0
	v_mov_b32_e32 v9, v0
	v_mov_b32_e32 v10, v0
	v_mov_b32_e32 v11, v0
	v_mov_b32_e32 v16, v0
	v_mov_b32_e32 v17, v0
	v_mov_b32_e32 v18, v0
	v_mov_b32_e32 v19, v0
	v_mov_b32_e32 v24, v0
	v_mov_b32_e32 v25, v0
	v_mov_b32_e32 v26, v0
	v_mov_b32_e32 v27, v0
	v_mov_b32_e32 v32, v0
	v_mov_b32_e32 v33, v0
	v_mov_b32_e32 v34, v0
	v_mov_b32_e32 v35, v0
	v_mov_b32_e32 v40, v0
	v_mov_b32_e32 v41, v0
	v_mov_b32_e32 v42, v0
	v_mov_b32_e32 v43, v0
	v_mov_b32_e32 v48, v0
	v_mov_b32_e32 v49, v0
	v_mov_b32_e32 v50, v0
	v_mov_b32_e32 v51, v0
	v_mov_b32_e32 v56, v0
	v_mov_b32_e32 v57, v0
	v_mov_b32_e32 v58, v0
	v_mov_b32_e32 v59, v0
	v_mov_b32_e32 v4, v0
	v_mov_b32_e32 v5, v0
	v_mov_b32_e32 v6, v0
	v_mov_b32_e32 v7, v0
	v_mov_b32_e32 v12, v0
	v_mov_b32_e32 v13, v0
	v_mov_b32_e32 v14, v0
	v_mov_b32_e32 v15, v0
	v_mov_b32_e32 v20, v0
	v_mov_b32_e32 v21, v0
	v_mov_b32_e32 v22, v0
	v_mov_b32_e32 v23, v0
	v_mov_b32_e32 v28, v0
	v_mov_b32_e32 v29, v0
	v_mov_b32_e32 v30, v0
	v_mov_b32_e32 v31, v0
	v_mov_b32_e32 v36, v0
	v_mov_b32_e32 v37, v0
	v_mov_b32_e32 v38, v0
	v_mov_b32_e32 v39, v0
	v_mov_b32_e32 v44, v0
	v_mov_b32_e32 v45, v0
	v_mov_b32_e32 v46, v0
	v_mov_b32_e32 v47, v0
	v_mov_b32_e32 v52, v0
	v_mov_b32_e32 v53, v0
	v_mov_b32_e32 v54, v0
	v_mov_b32_e32 v55, v0
	v_mov_b32_e32 v60, v0
	v_mov_b32_e32 v61, v0
	v_mov_b32_e32 v62, v0
	v_mov_b32_e32 v63, v0
	v_mov_b32_e32 v64, v0
	v_mov_b32_e32 v65, v0
	v_mov_b32_e32 v66, v0
	v_mov_b32_e32 v67, v0
	v_mov_b32_e32 v72, v0
	v_mov_b32_e32 v73, v0
	v_mov_b32_e32 v74, v0
	v_mov_b32_e32 v75, v0
	v_mov_b32_e32 v80, v0
	v_mov_b32_e32 v81, v0
	v_mov_b32_e32 v82, v0
	v_mov_b32_e32 v83, v0
	v_mov_b32_e32 v88, v0
	v_mov_b32_e32 v89, v0
	v_mov_b32_e32 v90, v0
	v_mov_b32_e32 v91, v0
	v_mov_b32_e32 v96, v0
	v_mov_b32_e32 v97, v0
	v_mov_b32_e32 v98, v0
	v_mov_b32_e32 v99, v0
	v_mov_b32_e32 v104, v0
	v_mov_b32_e32 v105, v0
	v_mov_b32_e32 v106, v0
	v_mov_b32_e32 v107, v0
	v_mov_b32_e32 v112, v0
	v_mov_b32_e32 v113, v0
	v_mov_b32_e32 v114, v0
	v_mov_b32_e32 v115, v0
	v_mov_b32_e32 v120, v0
	v_mov_b32_e32 v121, v0
	v_mov_b32_e32 v122, v0
	v_mov_b32_e32 v123, v0
	v_mov_b32_e32 v68, v0
	v_mov_b32_e32 v69, v0
	v_mov_b32_e32 v70, v0
	v_mov_b32_e32 v71, v0
	v_mov_b32_e32 v76, v0
	v_mov_b32_e32 v77, v0
	v_mov_b32_e32 v78, v0
	v_mov_b32_e32 v79, v0
	v_mov_b32_e32 v84, v0
	v_mov_b32_e32 v85, v0
	v_mov_b32_e32 v86, v0
	v_mov_b32_e32 v87, v0
	v_mov_b32_e32 v92, v0
	v_mov_b32_e32 v93, v0
	v_mov_b32_e32 v94, v0
	v_mov_b32_e32 v95, v0
	v_mov_b32_e32 v100, v0
	v_mov_b32_e32 v101, v0
	v_mov_b32_e32 v102, v0
	v_mov_b32_e32 v103, v0
	v_mov_b32_e32 v108, v0
	v_mov_b32_e32 v109, v0
	v_mov_b32_e32 v110, v0
	v_mov_b32_e32 v111, v0
	v_mov_b32_e32 v116, v0
	v_mov_b32_e32 v117, v0
	v_mov_b32_e32 v118, v0
	v_mov_b32_e32 v119, v0
	v_mov_b32_e32 v124, v0
	v_mov_b32_e32 v125, v0
	v_mov_b32_e32 v126, v0
	v_mov_b32_e32 v127, v0
	.p2align 6

;     __device__ bool next(int i, Unit& u) const { int pm, pn; if (!so.next(i, pm, pn)) return false; u.pm = pm; u.pn = pn; u.aoff = (unsigned)pm * BM * lda; u.boff = (unsigned)pn * BM * ldb; return true; }
;     __device__ __forceinline__ bool next(int i, Unit& u) const { int pm, pn; if (!so.next(i, pm, pn)) return false; u.pm = pm; u.pn = pn; u.aoff = (unsigned)pm * BM * lda; u.boff = (unsigned)(pm >> 4) * bstride + (unsigned)pn * BM * ldb; return true; }
;     __device__ __forceinline__ bool next(int i, Unit& u) const { int pm, pn; if (!so.next(i, pm, pn)) return false; u.pm = pm; u.pn = ((pn & 12) == 4 || (pn & 12) == 8) ? (pn ^ 12) : pn; u.aoff = (unsigned)pm * BM * lda; u.boff = (unsigned)pn * BM * ldb; return true; }
; template <class Epi, class Sched, bool ALIGN_EPI>
; __device__ __forceinline__ void gemm_phase(LAS unsigned char* lds, const Gemm g, const Sched& S, const Epi& E) {
;     ...
;         const bool has_next = S.next(ui + 1, nxt);
;         const char* nA = has_next ? (const char*)g.A + (size_t)nxt.aoff * 2 : cA; const char* nB = has_next ? (const char*)g.Bt + (size_t)nxt.boff * 2 : cB;
;     ...
;         for (int a = 0; a < 2; ++a)
; #pragma unroll
;             for (int b = 0; b < 2; ++b)
; #pragma unroll
;                 for (int m = 0; m < 4; ++m)
; #pragma unroll
;                     for (int n = 0; n < 2; ++n) acc[a][b][m][n] = (f32x4){0.f, 0.f, 0.f, 0.f};
.LBB0_844:
	s_lshl_b64 s[18:19], s[22:23], 1
	s_add_u32 s42, s6, s18
	s_addc_u32 s43, s7, s19
	s_and_b64 s[18:19], s[4:5], exec
	s_mov_b32 s41, s23
	s_cselect_b32 s81, s43, s59
	s_cselect_b32 s82, s42, s58
	s_lshl_b64 s[18:19], s[40:41], 1
	s_add_u32 s56, s54, s18
	s_addc_u32 s57, s55, s19
	s_and_b64 s[18:19], s[4:5], exec
	s_cselect_b32 s41, s57, s61
	s_cselect_b32 s83, s56, s60
	s_add_u32 s58, s58, 0x80080
	s_addc_u32 s59, s59, 0
	s_add_u32 s44, s60, 0x100
	v_mov_b32_e32 v0, 0
	s_addc_u32 s45, s61, 0
	s_mov_b32 s46, -2
	s_waitcnt lgkmcnt(0)
	v_mov_b32_e32 v1, v0
	v_mov_b32_e32 v2, v0
	v_mov_b32_e32 v3, v0
	v_mov_b32_e32 v4, v0
	v_mov_b32_e32 v5, v0
	v_mov_b32_e32 v6, v0
	v_mov_b32_e32 v7, v0
	v_mov_b32_e32 v16, v0
	v_mov_b32_e32 v17, v0
	v_mov_b32_e32 v18, v0
	v_mov_b32_e32 v19, v0
	v_mov_b32_e32 v20, v0
	v_mov_b32_e32 v21, v0
	v_mov_b32_e32 v22, v0
	v_mov_b32_e32 v23, v0
	v_mov_b32_e32 v32, v0
	v_mov_b32_e32 v33, v0
	v_mov_b32_e32 v34, v0
	v_mov_b32_e32 v35, v0
	v_mov_b32_e32 v36, v0
	v_mov_b32_e32 v37, v0
	v_mov_b32_e32 v38, v0
	v_mov_b32_e32 v39, v0
	v_mov_b32_e32 v48, v0
	v_mov_b32_e32 v49, v0
	v_mov_b32_e32 v50, v0
	v_mov_b32_e32 v51, v0
	v_mov_b32_e32 v52, v0
	v_mov_b32_e32 v53, v0
	v_mov_b32_e32 v54, v0
	v_mov_b32_e32 v55, v0
	v_mov_b32_e32 v8, v0
	v_mov_b32_e32 v9, v0
	v_mov_b32_e32 v10, v0
	v_mov_b32_e32 v11, v0
	v_mov_b32_e32 v12, v0
	v_mov_b32_e32 v13, v0
	v_mov_b32_e32 v14, v0
	v_mov_b32_e32 v15, v0
	v_mov_b32_e32 v24, v0
	v_mov_b32_e32 v25, v0
	v_mov_b32_e32 v26, v0
	v_mov_b32_e32 v27, v0
	v_mov_b32_e32 v28, v0
	v_mov_b32_e32 v29, v0
	v_mov_b32_e32 v30, v0
	v_mov_b32_e32 v31, v0
	v_mov_b32_e32 v40, v0
	v_mov_b32_e32 v41, v0
	v_mov_b32_e32 v42, v0
	v_mov_b32_e32 v43, v0
	v_mov_b32_e32 v44, v0
	v_mov_b32_e32 v45, v0
	v_mov_b32_e32 v46, v0
	v_mov_b32_e32 v47, v0
	v_mov_b32_e32 v56, v0
	v_mov_b32_e32 v57, v0
	v_mov_b32_e32 v58, v0
	v_mov_b32_e32 v59, v0
	v_mov_b32_e32 v60, v0
	v_mov_b32_e32 v61, v0
	v_mov_b32_e32 v62, v0
	v_mov_b32_e32 v63, v0
	v_mov_b32_e32 v64, v0
	v_mov_b32_e32 v65, v0
	v_mov_b32_e32 v66, v0
	v_mov_b32_e32 v67, v0
	v_mov_b32_e32 v68, v0
	v_mov_b32_e32 v69, v0
	v_mov_b32_e32 v70, v0
	v_mov_b32_e32 v71, v0
	v_mov_b32_e32 v80, v0
	v_mov_b32_e32 v81, v0
	v_mov_b32_e32 v82, v0
	v_mov_b32_e32 v83, v0
	v_mov_b32_e32 v84, v0
	v_mov_b32_e32 v85, v0
	v_mov_b32_e32 v86, v0
	v_mov_b32_e32 v87, v0
	v_mov_b32_e32 v96, v0
	v_mov_b32_e32 v97, v0
	v_mov_b32_e32 v98, v0
	v_mov_b32_e32 v99, v0
	v_mov_b32_e32 v100, v0
	v_mov_b32_e32 v101, v0
	v_mov_b32_e32 v102, v0
	v_mov_b32_e32 v103, v0
	v_mov_b32_e32 v112, v0
	v_mov_b32_e32 v113, v0
	v_mov_b32_e32 v114, v0
	v_mov_b32_e32 v115, v0
	v_mov_b32_e32 v116, v0
	v_mov_b32_e32 v117, v0
	v_mov_b32_e32 v118, v0
	v_mov_b32_e32 v119, v0
	v_mov_b32_e32 v72, v0
	v_mov_b32_e32 v73, v0
	v_mov_b32_e32 v74, v0
	v_mov_b32_e32 v75, v0
	v_mov_b32_e32 v76, v0
	v_mov_b32_e32 v77, v0
	v_mov_b32_e32 v78, v0
	v_mov_b32_e32 v79, v0
	v_mov_b32_e32 v88, v0
	v_mov_b32_e32 v89, v0
	v_mov_b32_e32 v90, v0
	v_mov_b32_e32 v91, v0
	v_mov_b32_e32 v92, v0
	v_mov_b32_e32 v93, v0
	v_mov_b32_e32 v94, v0
	v_mov_b32_e32 v95, v0
	v_mov_b32_e32 v104, v0
	v_mov_b32_e32 v105, v0
	v_mov_b32_e32 v106, v0
	v_mov_b32_e32 v107, v0
	v_mov_b32_e32 v108, v0
	v_mov_b32_e32 v109, v0
	v_mov_b32_e32 v110, v0
	v_mov_b32_e32 v111, v0
	v_mov_b32_e32 v120, v0
	v_mov_b32_e32 v121, v0
	v_mov_b32_e32 v122, v0
	v_mov_b32_e32 v123, v0
	v_mov_b32_e32 v124, v0
	v_mov_b32_e32 v125, v0
	v_mov_b32_e32 v126, v0
	v_mov_b32_e32 v127, v0
	.p2align 6

; #define PG8_STAGE(bufoff, gbase, voff) do { _Pragma("unroll") for (int _i = 0; _i < 2; ++_i) \
;         __builtin_amdgcn_global_load_lds((const unsigned*)((const char*)(gbase) + (voff)[_i]), (LAS unsigned*)(lds + (bufoff) + ldsw + _i * 8192), 16, 0, 0); } while (0)
; #define PG8_WAIT_V(n) asm volatile("s_waitcnt vmcnt(" #n ")" ::: "memory")
; #define PG8_BAR __builtin_amdgcn_s_barrier()
; template <class Epi, class Sched, bool ALIGN_EPI>
; __device__ __forceinline__ void gemm_phase(LAS unsigned char* lds, const Gemm g, const Sched& S, const Epi& E) {
;     ...
;     f32x4 acc[2][2][4][2];
; #pragma unroll
;     for (int a = 0; a < 2; ++a)
; #pragma unroll
;         for (int b = 0; b < 2; ++b)
; #pragma unroll
;             for (int m = 0; m < 4; ++m)
; #pragma unroll
;                 for (int n = 0; n < 2; ++n) acc[a][b][m][n] = (f32x4){0.f, 0.f, 0.f, 0.f};
;     ...
;     const char* cA = (const char*)g.A + (size_t)cur.aoff * 2; const char* cB = (const char*)g.Bt + (size_t)cur.boff * 2;
;     PG8_STAGE(PG8_SB(0, 0), cB, voffB); PG8_STAGE(PG8_SB(0, 1), cB + hB, voffB); PG8_STAGE(PG8_SA(0, 0), cA, voffA); PG8_STAGE(PG8_SA(0, 1), cA + hA, voffA);
;     if (wr == 1) PG8_BAR;
;     PG8_WAIT_V(2); PG8_BAR;
;     PG8_STAGE(PG8_SB(1, 0), cB + kstep, voffB); PG8_STAGE(PG8_SA(1, 0), cA + kstep, voffA); PG8_STAGE(PG8_SB(1, 1), cB + hB + kstep, voffB);
;     PG8_WAIT_V(6); PG8_BAR;
.LBB0_924:
	s_add_i32 m0, s22, 0x18000
	v_lshl_add_u64 v[0:1], v[0:1], 0, s[24:25]
	s_and_b32 s81, s11, 3
	s_lshl_b32 s11, s44, 6
	s_waitcnt vmcnt(2)
	s_barrier
	global_load_lds_dwordx4 v[0:1], off
	v_lshl_add_u64 v[0:1], v[2:3], 0, s[24:25]
	s_add_i32 m0, s22, 0x1a000
	s_add_i32 s90, s22, 0x8000
	s_add_i32 s91, s22, 0xa000
	global_load_lds_dwordx4 v[0:1], off
	v_lshl_add_u64 v[0:1], v[6:7], 0, s[24:25]
	s_mov_b32 m0, s90
	s_add_u32 s18, s56, 0x80080
	global_load_lds_dwordx4 v[0:1], off
	v_lshl_add_u64 v[0:1], v[4:5], 0, s[24:25]
	s_mov_b32 m0, s91
	s_addc_u32 s19, s57, 0
	global_load_lds_dwordx4 v[0:1], off
	s_add_i32 m0, s22, 0x1c000
	v_lshl_add_u64 v[0:1], s[18:19], 0, v[130:131]
	global_load_lds_dwordx4 v[0:1], off
	v_lshl_add_u64 v[0:1], s[18:19], 0, v[134:135]
	s_add_i32 m0, s22, 0x1e000
	v_mov_b32_e32 v127, 0
	global_load_lds_dwordx4 v[0:1], off
	s_waitcnt vmcnt(6)
	v_or_b32_e32 v165, s11, v145
	s_and_b64 vcc, exec, s[6:7]
	v_mov_b32_e32 v126, v127
	v_mov_b32_e32 v125, v127
	v_mov_b32_e32 v124, v127
	v_mov_b32_e32 v123, v127
	v_mov_b32_e32 v122, v127
	v_mov_b32_e32 v121, v127
	v_mov_b32_e32 v120, v127
	v_mov_b32_e32 v111, v127
	v_mov_b32_e32 v110, v127
	v_mov_b32_e32 v109, v127
	v_mov_b32_e32 v108, v127
	v_mov_b32_e32 v107, v127
	v_mov_b32_e32 v106, v127
	v_mov_b32_e32 v105, v127
	v_mov_b32_e32 v104, v127
	v_mov_b32_e32 v95, v127
	v_mov_b32_e32 v94, v127
	v_mov_b32_e32 v93, v127
	v_mov_b32_e32 v92, v127
	v_mov_b32_e32 v91, v127
	v_mov_b32_e32 v90, v127
	v_mov_b32_e32 v89, v127
	v_mov_b32_e32 v88, v127
	v_mov_b32_e32 v79, v127
	v_mov_b32_e32 v78, v127
	v_mov_b32_e32 v77, v127
	v_mov_b32_e32 v76, v127
	v_mov_b32_e32 v75, v127
	v_mov_b32_e32 v74, v127
	v_mov_b32_e32 v73, v127
	v_mov_b32_e32 v72, v127
	v_mov_b32_e32 v119, v127
	v_mov_b32_e32 v118, v127
	v_mov_b32_e32 v117, v127
	v_mov_b32_e32 v116, v127
	v_mov_b32_e32 v115, v127
	v_mov_b32_e32 v114, v127
	v_mov_b32_e32 v113, v127
	v_mov_b32_e32 v112, v127
	v_mov_b32_e32 v103, v127
	v_mov_b32_e32 v102, v127
	v_mov_b32_e32 v101, v127
	v_mov_b32_e32 v100, v127
	v_mov_b32_e32 v99, v127
	v_mov_b32_e32 v98, v127
	v_mov_b32_e32 v97, v127
	v_mov_b32_e32 v96, v127
	v_mov_b32_e32 v87, v127
	v_mov_b32_e32 v86, v127
	v_mov_b32_e32 v85, v127
	v_mov_b32_e32 v84, v127
	v_mov_b32_e32 v83, v127
	v_mov_b32_e32 v82, v127
	v_mov_b32_e32 v81, v127
	v_mov_b32_e32 v80, v127
	v_mov_b32_e32 v71, v127
	v_mov_b32_e32 v70, v127
	v_mov_b32_e32 v69, v127
	v_mov_b32_e32 v68, v127
	v_mov_b32_e32 v67, v127
	v_mov_b32_e32 v66, v127
	v_mov_b32_e32 v65, v127
	v_mov_b32_e32 v64, v127
	v_mov_b32_e32 v63, v127
	v_mov_b32_e32 v62, v127
	v_mov_b32_e32 v61, v127
	v_mov_b32_e32 v60, v127
	v_mov_b32_e32 v59, v127
	v_mov_b32_e32 v58, v127
	v_mov_b32_e32 v57, v127
	v_mov_b32_e32 v56, v127
	v_mov_b32_e32 v47, v127
	v_mov_b32_e32 v46, v127
	v_mov_b32_e32 v45, v127
	v_mov_b32_e32 v44, v127
	v_mov_b32_e32 v43, v127
	v_mov_b32_e32 v42, v127
	v_mov_b32_e32 v41, v127
	v_mov_b32_e32 v40, v127
	v_mov_b32_e32 v31, v127
	v_mov_b32_e32 v30, v127
	v_mov_b32_e32 v29, v127
	v_mov_b32_e32 v28, v127
	v_mov_b32_e32 v27, v127
	v_mov_b32_e32 v26, v127
	v_mov_b32_e32 v25, v127
	v_mov_b32_e32 v24, v127
	v_mov_b32_e32 v15, v127
	v_mov_b32_e32 v14, v127
	v_mov_b32_e32 v13, v127
	v_mov_b32_e32 v12, v127
	v_mov_b32_e32 v11, v127
	v_mov_b32_e32 v10, v127
	v_mov_b32_e32 v9, v127
	v_mov_b32_e32 v8, v127
	v_mov_b32_e32 v55, v127
	v_mov_b32_e32 v54, v127
	v_mov_b32_e32 v53, v127
	v_mov_b32_e32 v52, v127
	v_mov_b32_e32 v51, v127
	v_mov_b32_e32 v50, v127
	v_mov_b32_e32 v49, v127
	v_mov_b32_e32 v48, v127
	v_mov_b32_e32 v39, v127
	v_mov_b32_e32 v38, v127
	v_mov_b32_e32 v37, v127
	v_mov_b32_e32 v36, v127
	v_mov_b32_e32 v35, v127
	v_mov_b32_e32 v34, v127
	v_mov_b32_e32 v33, v127
	v_mov_b32_e32 v32, v127
	v_mov_b32_e32 v23, v127
	v_mov_b32_e32 v22, v127
	v_mov_b32_e32 v21, v127
	v_mov_b32_e32 v20, v127
	v_mov_b32_e32 v19, v127
	v_mov_b32_e32 v18, v127
	v_mov_b32_e32 v17, v127
	v_mov_b32_e32 v16, v127
	v_mov_b32_e32 v7, v127
	v_mov_b32_e32 v6, v127
	v_mov_b32_e32 v5, v127
	v_mov_b32_e32 v4, v127
	v_mov_b32_e32 v3, v127
	v_mov_b32_e32 v2, v127
	v_mov_b32_e32 v1, v127
	v_mov_b32_e32 v0, v127
	s_barrier
; template <class Epi, class Sched, bool ALIGN_EPI>
; __device__ __forceinline__ void gemm_phase(LAS unsigned char* lds, const Gemm g, const Sched& S, const Epi& E) {
;     ...
;     for (int i = 0; i < 2; ++i) { int R, C; stage_rc(tid * 16 + i * 8192, R, C); const int Rb = Epi::PERM ? ((R & ~31) + perm32(R & 31)) : R;
;         voffA[i] = (unsigned)(R * g.lda + C) * 2u; voffB[i] = (unsigned)(Rb * g.ldb + C) * 2u; }
;     const size_t kstep = (size_t)(BK * 2);
;     const size_t hA = (size_t)HALF * g.lda * 2, hB = (size_t)HALF * g.ldb * 2;
;     const unsigned ldsw = (unsigned)wid * 1024u;
;     const int aoff = lds_byte(wr * 64 + fr, fq * 8), boff = lds_byte(wc * 32 + fr, fq * 8);
;     ...
;     f32x4 acc[2][2][4][2];
; #pragma unroll
;     for (int a = 0; a < 2; ++a)
; #pragma unroll
;         for (int b = 0; b < 2; ++b)
; #pragma unroll
;             for (int m = 0; m < 4; ++m)
; #pragma unroll
;                 for (int n = 0; n < 2; ++n) acc[a][b][m][n] = (f32x4){0.f, 0.f, 0.f, 0.f};
	s_cbranch_vccnz .LBB0_928
	v_lshlrev_b32_e32 v0, 6, v165
	v_lshlrev_b32_e32 v1, 2, v165
	v_and_or_b32 v0, v0, s67, v162
	v_and_b32_e32 v1, 32, v1
	s_lshl_b32 s18, s44, 13
	v_lshl_or_b32 v2, s81, 12, v163
	v_bitop3_b32 v1, v0, s18, v1 bitop3:0xde
	v_mov_b32_e32 v0, 0
	s_add_i32 s46, s70, s84
	s_add_i32 s92, s71, s84
	v_lshl_add_u64 v[146:147], v[140:141], 0, s[60:61]
	v_lshl_add_u64 v[148:149], v[142:143], 0, s[60:61]
	s_mov_b32 s62, 0
	s_mov_b64 s[60:61], 0xc580080
	v_add_u32_e32 v150, s70, v2
	v_add_u32_e32 v151, s71, v2
	v_add_u32_e32 v152, 0, v1
	s_add_i32 s44, s22, 0xc000
	s_add_i32 s45, s22, 0xe000
	s_add_i32 s47, s46, 0x2000
	s_add_i32 s93, s92, 0x2000
	v_add_u32_e32 v153, s74, v2
	v_add_u32_e32 v154, s75, v2
	v_mov_b32_e32 v1, v0
	v_mov_b32_e32 v2, v0
	v_mov_b32_e32 v3, v0
	v_mov_b32_e32 v4, v0
	v_mov_b32_e32 v5, v0
	v_mov_b32_e32 v6, v0
	v_mov_b32_e32 v7, v0
	v_mov_b32_e32 v16, v0
	v_mov_b32_e32 v17, v0
	v_mov_b32_e32 v18, v0
	v_mov_b32_e32 v19, v0
	v_mov_b32_e32 v20, v0
	v_mov_b32_e32 v21, v0
	v_mov_b32_e32 v22, v0
	v_mov_b32_e32 v23, v0
	v_mov_b32_e32 v32, v0
	v_mov_b32_e32 v33, v0
	v_mov_b32_e32 v34, v0
	v_mov_b32_e32 v35, v0
	v_mov_b32_e32 v36, v0
	v_mov_b32_e32 v37, v0
	v_mov_b32_e32 v38, v0
	v_mov_b32_e32 v39, v0
	v_mov_b32_e32 v48, v0
	v_mov_b32_e32 v49, v0
	v_mov_b32_e32 v50, v0
	v_mov_b32_e32 v51, v0
	v_mov_b32_e32 v52, v0
	v_mov_b32_e32 v53, v0
	v_mov_b32_e32 v54, v0
	v_mov_b32_e32 v55, v0
	v_mov_b32_e32 v8, v0
	v_mov_b32_e32 v9, v0
	v_mov_b32_e32 v10, v0
	v_mov_b32_e32 v11, v0
	v_mov_b32_e32 v12, v0
	v_mov_b32_e32 v13, v0
	v_mov_b32_e32 v14, v0
	v_mov_b32_e32 v15, v0
	v_mov_b32_e32 v24, v0
	v_mov_b32_e32 v25, v0
	v_mov_b32_e32 v26, v0
	v_mov_b32_e32 v27, v0
	v_mov_b32_e32 v28, v0
	v_mov_b32_e32 v29, v0
	v_mov_b32_e32 v30, v0
	v_mov_b32_e32 v31, v0
	v_mov_b32_e32 v40, v0
	v_mov_b32_e32 v41, v0
	v_mov_b32_e32 v42, v0
	v_mov_b32_e32 v43, v0
	v_mov_b32_e32 v44, v0
	v_mov_b32_e32 v45, v0
	v_mov_b32_e32 v46, v0
	v_mov_b32_e32 v47, v0
	v_mov_b32_e32 v56, v0
	v_mov_b32_e32 v57, v0
	v_mov_b32_e32 v58, v0
	v_mov_b32_e32 v59, v0
	v_mov_b32_e32 v60, v0
	v_mov_b32_e32 v61, v0
	v_mov_b32_e32 v62, v0
	v_mov_b32_e32 v63, v0
	v_mov_b32_e32 v64, v0
	v_mov_b32_e32 v65, v0
	v_mov_b32_e32 v66, v0
	v_mov_b32_e32 v67, v0
	v_mov_b32_e32 v68, v0
	v_mov_b32_e32 v69, v0
	v_mov_b32_e32 v70, v0
	v_mov_b32_e32 v71, v0
	v_mov_b32_e32 v80, v0
	v_mov_b32_e32 v81, v0
	v_mov_b32_e32 v82, v0
	v_mov_b32_e32 v83, v0
	v_mov_b32_e32 v84, v0
	v_mov_b32_e32 v85, v0
	v_mov_b32_e32 v86, v0
	v_mov_b32_e32 v87, v0
	v_mov_b32_e32 v96, v0
	v_mov_b32_e32 v97, v0
	v_mov_b32_e32 v98, v0
	v_mov_b32_e32 v99, v0
	v_mov_b32_e32 v100, v0
	v_mov_b32_e32 v101, v0
	v_mov_b32_e32 v102, v0
	v_mov_b32_e32 v103, v0
	v_mov_b32_e32 v112, v0
	v_mov_b32_e32 v113, v0
	v_mov_b32_e32 v114, v0
	v_mov_b32_e32 v115, v0
	v_mov_b32_e32 v116, v0
	v_mov_b32_e32 v117, v0
	v_mov_b32_e32 v118, v0
	v_mov_b32_e32 v119, v0
	v_mov_b32_e32 v72, v0
	v_mov_b32_e32 v73, v0
	v_mov_b32_e32 v74, v0
	v_mov_b32_e32 v75, v0
	v_mov_b32_e32 v76, v0
	v_mov_b32_e32 v77, v0
	v_mov_b32_e32 v78, v0
	v_mov_b32_e32 v79, v0
	v_mov_b32_e32 v88, v0
	v_mov_b32_e32 v89, v0
	v_mov_b32_e32 v90, v0
	v_mov_b32_e32 v91, v0
	v_mov_b32_e32 v92, v0
	v_mov_b32_e32 v93, v0
	v_mov_b32_e32 v94, v0
	v_mov_b32_e32 v95, v0
	v_mov_b32_e32 v104, v0
	v_mov_b32_e32 v105, v0
	v_mov_b32_e32 v106, v0
	v_mov_b32_e32 v107, v0
	v_mov_b32_e32 v108, v0
	v_mov_b32_e32 v109, v0
	v_mov_b32_e32 v110, v0
	v_mov_b32_e32 v111, v0
	v_mov_b32_e32 v120, v0
	v_mov_b32_e32 v121, v0
	v_mov_b32_e32 v122, v0
	v_mov_b32_e32 v123, v0
	v_mov_b32_e32 v124, v0
	v_mov_b32_e32 v125, v0
	v_mov_b32_e32 v126, v0
	v_mov_b32_e32 v127, v0
	.p2align 6

; #define PG8_STAGE(bufoff, gbase, voff) do { _Pragma("unroll") for (int _i = 0; _i < 2; ++_i) \
;         __builtin_amdgcn_global_load_lds((const unsigned*)((const char*)(gbase) + (voff)[_i]), (LAS unsigned*)(lds + (bufoff) + ldsw + _i * 8192), 16, 0, 0); } while (0)
; #define PG8_WAIT_V(n) asm volatile("s_waitcnt vmcnt(" #n ")" ::: "memory")
; #define PG8_BAR __builtin_amdgcn_s_barrier()
; template <class Epi, class Sched, bool ALIGN_EPI>
; __device__ __forceinline__ void gemm_phase(LAS unsigned char* lds, const Gemm g, const Sched& S, const Epi& E) {
;     ...
;     f32x4 acc[2][2][4][2];
; #pragma unroll
;     for (int a = 0; a < 2; ++a)
; #pragma unroll
;         for (int b = 0; b < 2; ++b)
; #pragma unroll
;             for (int m = 0; m < 4; ++m)
; #pragma unroll
;                 for (int n = 0; n < 2; ++n) acc[a][b][m][n] = (f32x4){0.f, 0.f, 0.f, 0.f};
;     ...
;     const char* cA = (const char*)g.A + (size_t)cur.aoff * 2; const char* cB = (const char*)g.Bt + (size_t)cur.boff * 2;
;     PG8_STAGE(PG8_SB(0, 0), cB, voffB); PG8_STAGE(PG8_SB(0, 1), cB + hB, voffB); PG8_STAGE(PG8_SA(0, 0), cA, voffA); PG8_STAGE(PG8_SA(0, 1), cA + hA, voffA);
;     if (wr == 1) PG8_BAR;
;     PG8_WAIT_V(2); PG8_BAR;
;     PG8_STAGE(PG8_SB(1, 0), cB + kstep, voffB); PG8_STAGE(PG8_SA(1, 0), cA + kstep, voffA); PG8_STAGE(PG8_SB(1, 1), cB + hB + kstep, voffB);
;     PG8_WAIT_V(6); PG8_BAR;
.LBB0_953:
	s_lshl_b32 s4, s39, 5
	s_add_i32 m0, s23, 0x18000
	v_lshl_add_u64 v[0:1], v[0:1], 0, s[6:7]
	s_and_b32 s65, s4, 0x60
	s_waitcnt vmcnt(2)
	s_barrier
	global_load_lds_dwordx4 v[0:1], off
	v_lshl_add_u64 v[0:1], v[2:3], 0, s[6:7]
	s_add_i32 m0, s23, 0x1a000
	s_add_i32 s70, s23, 0x8000
	s_add_i32 s71, s23, 0xa000
	global_load_lds_dwordx4 v[0:1], off
	v_lshl_add_u64 v[0:1], v[6:7], 0, s[6:7]
	s_mov_b32 m0, s70
	s_add_u32 s18, s24, 0x100080
	global_load_lds_dwordx4 v[0:1], off
	v_lshl_add_u64 v[0:1], v[4:5], 0, s[6:7]
	s_mov_b32 m0, s71
	s_addc_u32 s19, s25, 0
	global_load_lds_dwordx4 v[0:1], off
	s_add_i32 m0, s23, 0x1c000
	v_lshl_add_u64 v[0:1], s[18:19], 0, v[130:131]
	global_load_lds_dwordx4 v[0:1], off
	v_lshl_add_u64 v[0:1], s[18:19], 0, v[134:135]
	s_add_i32 m0, s23, 0x1e000
	v_mov_b32_e32 v127, 0
	global_load_lds_dwordx4 v[0:1], off
	s_waitcnt vmcnt(6)
	v_lshl_or_b32 v136, s38, 6, v146
	s_and_b64 vcc, exec, s[2:3]
	v_mov_b32_e32 v126, v127
	v_mov_b32_e32 v125, v127
	v_mov_b32_e32 v124, v127
	v_mov_b32_e32 v123, v127
	v_mov_b32_e32 v122, v127
	v_mov_b32_e32 v121, v127
	v_mov_b32_e32 v120, v127
	v_mov_b32_e32 v111, v127
	v_mov_b32_e32 v110, v127
	v_mov_b32_e32 v109, v127
	v_mov_b32_e32 v108, v127
	v_mov_b32_e32 v107, v127
	v_mov_b32_e32 v106, v127
	v_mov_b32_e32 v105, v127
	v_mov_b32_e32 v104, v127
	v_mov_b32_e32 v95, v127
	v_mov_b32_e32 v94, v127
	v_mov_b32_e32 v93, v127
	v_mov_b32_e32 v92, v127
	v_mov_b32_e32 v91, v127
	v_mov_b32_e32 v90, v127
	v_mov_b32_e32 v89, v127
	v_mov_b32_e32 v88, v127
	v_mov_b32_e32 v79, v127
	v_mov_b32_e32 v78, v127
	v_mov_b32_e32 v77, v127
	v_mov_b32_e32 v76, v127
	v_mov_b32_e32 v75, v127
	v_mov_b32_e32 v74, v127
	v_mov_b32_e32 v73, v127
	v_mov_b32_e32 v72, v127
	v_mov_b32_e32 v119, v127
	v_mov_b32_e32 v118, v127
	v_mov_b32_e32 v117, v127
	v_mov_b32_e32 v116, v127
	v_mov_b32_e32 v115, v127
	v_mov_b32_e32 v114, v127
	v_mov_b32_e32 v113, v127
	v_mov_b32_e32 v112, v127
	v_mov_b32_e32 v103, v127
	v_mov_b32_e32 v102, v127
	v_mov_b32_e32 v101, v127
	v_mov_b32_e32 v100, v127
	v_mov_b32_e32 v99, v127
	v_mov_b32_e32 v98, v127
	v_mov_b32_e32 v97, v127
	v_mov_b32_e32 v96, v127
	v_mov_b32_e32 v87, v127
	v_mov_b32_e32 v86, v127
	v_mov_b32_e32 v85, v127
	v_mov_b32_e32 v84, v127
	v_mov_b32_e32 v83, v127
	v_mov_b32_e32 v82, v127
	v_mov_b32_e32 v81, v127
	v_mov_b32_e32 v80, v127
	v_mov_b32_e32 v71, v127
	v_mov_b32_e32 v70, v127
	v_mov_b32_e32 v69, v127
	v_mov_b32_e32 v68, v127
	v_mov_b32_e32 v67, v127
	v_mov_b32_e32 v66, v127
	v_mov_b32_e32 v65, v127
	v_mov_b32_e32 v64, v127
	v_mov_b32_e32 v63, v127
	v_mov_b32_e32 v62, v127
	v_mov_b32_e32 v61, v127
	v_mov_b32_e32 v60, v127
	v_mov_b32_e32 v59, v127
	v_mov_b32_e32 v58, v127
	v_mov_b32_e32 v57, v127
	v_mov_b32_e32 v56, v127
	v_mov_b32_e32 v47, v127
	v_mov_b32_e32 v46, v127
	v_mov_b32_e32 v45, v127
	v_mov_b32_e32 v44, v127
	v_mov_b32_e32 v43, v127
	v_mov_b32_e32 v42, v127
	v_mov_b32_e32 v41, v127
	v_mov_b32_e32 v40, v127
	v_mov_b32_e32 v31, v127
	v_mov_b32_e32 v30, v127
	v_mov_b32_e32 v29, v127
	v_mov_b32_e32 v28, v127
	v_mov_b32_e32 v27, v127
	v_mov_b32_e32 v26, v127
	v_mov_b32_e32 v25, v127
	v_mov_b32_e32 v24, v127
	v_mov_b32_e32 v15, v127
	v_mov_b32_e32 v14, v127
	v_mov_b32_e32 v13, v127
	v_mov_b32_e32 v12, v127
	v_mov_b32_e32 v11, v127
	v_mov_b32_e32 v10, v127
	v_mov_b32_e32 v9, v127
	v_mov_b32_e32 v8, v127
	v_mov_b32_e32 v55, v127
	v_mov_b32_e32 v54, v127
	v_mov_b32_e32 v53, v127
	v_mov_b32_e32 v52, v127
	v_mov_b32_e32 v51, v127
	v_mov_b32_e32 v50, v127
	v_mov_b32_e32 v49, v127
	v_mov_b32_e32 v48, v127
	v_mov_b32_e32 v39, v127
	v_mov_b32_e32 v38, v127
	v_mov_b32_e32 v37, v127
	v_mov_b32_e32 v36, v127
	v_mov_b32_e32 v35, v127
	v_mov_b32_e32 v34, v127
	v_mov_b32_e32 v33, v127
	v_mov_b32_e32 v32, v127
	v_mov_b32_e32 v23, v127
	v_mov_b32_e32 v22, v127
	v_mov_b32_e32 v21, v127
	v_mov_b32_e32 v20, v127
	v_mov_b32_e32 v19, v127
	v_mov_b32_e32 v18, v127
	v_mov_b32_e32 v17, v127
	v_mov_b32_e32 v16, v127
	v_mov_b32_e32 v7, v127
	v_mov_b32_e32 v6, v127
	v_mov_b32_e32 v5, v127
	v_mov_b32_e32 v4, v127
	v_mov_b32_e32 v3, v127
	v_mov_b32_e32 v2, v127
	v_mov_b32_e32 v1, v127
	v_mov_b32_e32 v0, v127
	s_barrier
; template <class Epi, class Sched, bool ALIGN_EPI>
; __device__ __forceinline__ void gemm_phase(LAS unsigned char* lds, const Gemm g, const Sched& S, const Epi& E) {
;     ...
;     for (int i = 0; i < 2; ++i) { int R, C; stage_rc(tid * 16 + i * 8192, R, C); const int Rb = Epi::PERM ? ((R & ~31) + perm32(R & 31)) : R;
;         voffA[i] = (unsigned)(R * g.lda + C) * 2u; voffB[i] = (unsigned)(Rb * g.ldb + C) * 2u; }
;     const size_t kstep = (size_t)(BK * 2);
;     const size_t hA = (size_t)HALF * g.lda * 2, hB = (size_t)HALF * g.ldb * 2;
;     const unsigned ldsw = (unsigned)wid * 1024u;
;     const int aoff = lds_byte(wr * 64 + fr, fq * 8), boff = lds_byte(wc * 32 + fr, fq * 8);
;     ...
;     f32x4 acc[2][2][4][2];
; #pragma unroll
;     for (int a = 0; a < 2; ++a)
; #pragma unroll
;         for (int b = 0; b < 2; ++b)
; #pragma unroll
;             for (int m = 0; m < 4; ++m)
; #pragma unroll
;                 for (int n = 0; n < 2; ++n) acc[a][b][m][n] = (f32x4){0.f, 0.f, 0.f, 0.f};
	s_cbranch_vccnz .LBB0_956
	s_lshr_b32 s4, s54, 3
	s_and_b32 s18, s58, 7
	s_and_b32 s4, s4, 3
	s_lshl_b32 s18, s18, 20
	s_lshl_b32 s4, s4, 10
	s_or_b32 s4, s18, s4
	v_lshlrev_b32_e32 v0, 6, v136
	v_lshlrev_b32_e32 v1, 2, v136
	v_lshl_add_u64 v[142:143], v[138:139], 0, s[4:5]
	v_lshl_add_u64 v[144:145], v[140:141], 0, s[4:5]
	v_and_or_b32 v0, v0, s55, v148
	v_and_b32_e32 v1, 32, v1
	s_lshl_b32 s4, s38, 13
	v_lshl_or_b32 v150, s65, 7, v149
	v_bitop3_b32 v1, v0, s4, v1 bitop3:0xde
	v_mov_b32_e32 v0, 0
	s_add_i32 s45, s59, s11
	s_add_i32 s47, s60, s11
	s_mov_b32 s40, 0
	s_mov_b64 s[38:39], 0xb480080
	v_add_u32_e32 v151, 0, v1
	v_add_u32_e32 v152, s59, v150
	v_add_u32_e32 v153, s60, v150
	s_add_i32 s4, s23, 0xc000
	s_add_i32 s44, s23, 0xe000
	s_add_i32 s46, s45, 0x2000
	s_add_i32 s74, s47, 0x2000
	v_add_u32_e32 v154, s61, v150
	v_mov_b32_e32 v1, v0
	v_mov_b32_e32 v2, v0
	v_mov_b32_e32 v3, v0
	v_mov_b32_e32 v4, v0
	v_mov_b32_e32 v5, v0
	v_mov_b32_e32 v6, v0
	v_mov_b32_e32 v7, v0
	v_mov_b32_e32 v16, v0
	v_mov_b32_e32 v17, v0
	v_mov_b32_e32 v18, v0
	v_mov_b32_e32 v19, v0
	v_mov_b32_e32 v20, v0
	v_mov_b32_e32 v21, v0
	v_mov_b32_e32 v22, v0
	v_mov_b32_e32 v23, v0
	v_mov_b32_e32 v32, v0
	v_mov_b32_e32 v33, v0
	v_mov_b32_e32 v34, v0
	v_mov_b32_e32 v35, v0
	v_mov_b32_e32 v36, v0
	v_mov_b32_e32 v37, v0
	v_mov_b32_e32 v38, v0
	v_mov_b32_e32 v39, v0
	v_mov_b32_e32 v48, v0
	v_mov_b32_e32 v49, v0
	v_mov_b32_e32 v50, v0
	v_mov_b32_e32 v51, v0
	v_mov_b32_e32 v52, v0
	v_mov_b32_e32 v53, v0
	v_mov_b32_e32 v54, v0
	v_mov_b32_e32 v55, v0
	v_mov_b32_e32 v8, v0
	v_mov_b32_e32 v9, v0
	v_mov_b32_e32 v10, v0
	v_mov_b32_e32 v11, v0
	v_mov_b32_e32 v12, v0
	v_mov_b32_e32 v13, v0
	v_mov_b32_e32 v14, v0
	v_mov_b32_e32 v15, v0
	v_mov_b32_e32 v24, v0
	v_mov_b32_e32 v25, v0
	v_mov_b32_e32 v26, v0
	v_mov_b32_e32 v27, v0
	v_mov_b32_e32 v28, v0
	v_mov_b32_e32 v29, v0
	v_mov_b32_e32 v30, v0
	v_mov_b32_e32 v31, v0
	v_mov_b32_e32 v40, v0
	v_mov_b32_e32 v41, v0
	v_mov_b32_e32 v42, v0
	v_mov_b32_e32 v43, v0
	v_mov_b32_e32 v44, v0
	v_mov_b32_e32 v45, v0
	v_mov_b32_e32 v46, v0
	v_mov_b32_e32 v47, v0
	v_mov_b32_e32 v56, v0
	v_mov_b32_e32 v57, v0
	v_mov_b32_e32 v58, v0
	v_mov_b32_e32 v59, v0
	v_mov_b32_e32 v60, v0
	v_mov_b32_e32 v61, v0
	v_mov_b32_e32 v62, v0
	v_mov_b32_e32 v63, v0
	v_mov_b32_e32 v64, v0
	v_mov_b32_e32 v65, v0
	v_mov_b32_e32 v66, v0
	v_mov_b32_e32 v67, v0
	v_mov_b32_e32 v68, v0
	v_mov_b32_e32 v69, v0
	v_mov_b32_e32 v70, v0
	v_mov_b32_e32 v71, v0
	v_mov_b32_e32 v80, v0
	v_mov_b32_e32 v81, v0
	v_mov_b32_e32 v82, v0
	v_mov_b32_e32 v83, v0
	v_mov_b32_e32 v84, v0
	v_mov_b32_e32 v85, v0
	v_mov_b32_e32 v86, v0
	v_mov_b32_e32 v87, v0
	v_mov_b32_e32 v96, v0
	v_mov_b32_e32 v97, v0
	v_mov_b32_e32 v98, v0
	v_mov_b32_e32 v99, v0
	v_mov_b32_e32 v100, v0
	v_mov_b32_e32 v101, v0
	v_mov_b32_e32 v102, v0
	v_mov_b32_e32 v103, v0
	v_mov_b32_e32 v112, v0
	v_mov_b32_e32 v113, v0
	v_mov_b32_e32 v114, v0
	v_mov_b32_e32 v115, v0
	v_mov_b32_e32 v116, v0
	v_mov_b32_e32 v117, v0
	v_mov_b32_e32 v118, v0
	v_mov_b32_e32 v119, v0
	v_mov_b32_e32 v72, v0
	v_mov_b32_e32 v73, v0
	v_mov_b32_e32 v74, v0
	v_mov_b32_e32 v75, v0
	v_mov_b32_e32 v76, v0
	v_mov_b32_e32 v77, v0
	v_mov_b32_e32 v78, v0
	v_mov_b32_e32 v79, v0
	v_mov_b32_e32 v88, v0
	v_mov_b32_e32 v89, v0
	v_mov_b32_e32 v90, v0
	v_mov_b32_e32 v91, v0
	v_mov_b32_e32 v92, v0
	v_mov_b32_e32 v93, v0
	v_mov_b32_e32 v94, v0
	v_mov_b32_e32 v95, v0
	v_mov_b32_e32 v104, v0
	v_mov_b32_e32 v105, v0
	v_mov_b32_e32 v106, v0
	v_mov_b32_e32 v107, v0
	v_mov_b32_e32 v108, v0
	v_mov_b32_e32 v109, v0
	v_mov_b32_e32 v110, v0
	v_mov_b32_e32 v111, v0
	v_mov_b32_e32 v120, v0
	v_mov_b32_e32 v121, v0
	v_mov_b32_e32 v122, v0
	v_mov_b32_e32 v123, v0
	v_mov_b32_e32 v124, v0
	v_mov_b32_e32 v125, v0
	v_mov_b32_e32 v126, v0
	v_mov_b32_e32 v127, v0
	.p2align 6

;     __device__ bool next(int i, Unit& u) const { int pm, pn; if (!so.next(i, pm, pn)) return false; u.pm = pm; u.pn = pn; u.aoff = (unsigned)pm * BM * lda; u.boff = (unsigned)pn * BM * ldb; return true; }
;     __device__ __forceinline__ bool next(int i, Unit& u) const { int pm, pn; if (!so.next(i, pm, pn)) return false; u.pm = pm; u.pn = pn; u.aoff = (unsigned)pm * BM * lda; u.boff = (unsigned)(pm >> 4) * bstride + (unsigned)pn * BM * ldb; return true; }
;     __device__ __forceinline__ bool next(int i, Unit& u) const { int pm, pn; if (!so.next(i, pm, pn)) return false; u.pm = pm; u.pn = ((pn & 12) == 4 || (pn & 12) == 8) ? (pn ^ 12) : pn; u.aoff = (unsigned)pm * BM * lda; u.boff = (unsigned)pn * BM * ldb; return true; }
; template <class Epi, class Sched, bool ALIGN_EPI>
; __device__ __forceinline__ void gemm_phase(LAS unsigned char* lds, const Gemm g, const Sched& S, const Epi& E) {
;     ...
;         const bool has_next = S.next(ui + 1, nxt);
;         const char* nA = has_next ? (const char*)g.A + (size_t)nxt.aoff * 2 : cA; const char* nB = has_next ? (const char*)g.Bt + (size_t)nxt.boff * 2 : cB;
;     ...
;         for (int a = 0; a < 2; ++a)
; #pragma unroll
;             for (int b = 0; b < 2; ++b)
; #pragma unroll
;                 for (int m = 0; m < 4; ++m)
; #pragma unroll
;                     for (int n = 0; n < 2; ++n) acc[a][b][m][n] = (f32x4){0.f, 0.f, 0.f, 0.f};
.LBB0_1063:
	s_lshl_b64 s[18:19], s[20:21], 1
	s_add_u32 s40, s36, s18
	s_mov_b32 s39, s21
	s_addc_u32 s41, s37, s19
	s_lshl_b64 s[18:19], s[38:39], 1
	s_add_u32 s42, s72, s18
	v_mov_b32_e32 v127, 0
	s_addc_u32 s43, s73, s19
	s_andn2_b64 vcc, exec, s[26:27]
	v_mov_b32_e32 v126, v127
	v_mov_b32_e32 v125, v127
	v_mov_b32_e32 v124, v127
	v_mov_b32_e32 v123, v127
	v_mov_b32_e32 v122, v127
	v_mov_b32_e32 v121, v127
	v_mov_b32_e32 v120, v127
	v_mov_b32_e32 v111, v127
	v_mov_b32_e32 v110, v127
	v_mov_b32_e32 v109, v127
	v_mov_b32_e32 v108, v127
	v_mov_b32_e32 v107, v127
	v_mov_b32_e32 v106, v127
	v_mov_b32_e32 v105, v127
	v_mov_b32_e32 v104, v127
	v_mov_b32_e32 v95, v127
	v_mov_b32_e32 v94, v127
	v_mov_b32_e32 v93, v127
	v_mov_b32_e32 v92, v127
	v_mov_b32_e32 v91, v127
	v_mov_b32_e32 v90, v127
	v_mov_b32_e32 v89, v127
	v_mov_b32_e32 v88, v127
	v_mov_b32_e32 v79, v127
	v_mov_b32_e32 v78, v127
	v_mov_b32_e32 v77, v127
	v_mov_b32_e32 v76, v127
	v_mov_b32_e32 v75, v127
	v_mov_b32_e32 v74, v127
	v_mov_b32_e32 v73, v127
	v_mov_b32_e32 v72, v127
	v_mov_b32_e32 v119, v127
	v_mov_b32_e32 v118, v127
	v_mov_b32_e32 v117, v127
	v_mov_b32_e32 v116, v127
	v_mov_b32_e32 v115, v127
	v_mov_b32_e32 v114, v127
	v_mov_b32_e32 v113, v127
	v_mov_b32_e32 v112, v127
	v_mov_b32_e32 v103, v127
	v_mov_b32_e32 v102, v127
	v_mov_b32_e32 v101, v127
	v_mov_b32_e32 v100, v127
	v_mov_b32_e32 v99, v127
	v_mov_b32_e32 v98, v127
	v_mov_b32_e32 v97, v127
	v_mov_b32_e32 v96, v127
	v_mov_b32_e32 v87, v127
	v_mov_b32_e32 v86, v127
	v_mov_b32_e32 v85, v127
	v_mov_b32_e32 v84, v127
	v_mov_b32_e32 v83, v127
	v_mov_b32_e32 v82, v127
	v_mov_b32_e32 v81, v127
	v_mov_b32_e32 v80, v127
	v_mov_b32_e32 v71, v127
	v_mov_b32_e32 v70, v127
	v_mov_b32_e32 v69, v127
	v_mov_b32_e32 v68, v127
	v_mov_b32_e32 v67, v127
	v_mov_b32_e32 v66, v127
	v_mov_b32_e32 v65, v127
	v_mov_b32_e32 v64, v127
	v_mov_b32_e32 v63, v127
	v_mov_b32_e32 v62, v127
	v_mov_b32_e32 v61, v127
	v_mov_b32_e32 v60, v127
	v_mov_b32_e32 v59, v127
	v_mov_b32_e32 v58, v127
	v_mov_b32_e32 v57, v127
	v_mov_b32_e32 v56, v127
	v_mov_b32_e32 v47, v127
	v_mov_b32_e32 v46, v127
	v_mov_b32_e32 v45, v127
	v_mov_b32_e32 v44, v127
	v_mov_b32_e32 v43, v127
	v_mov_b32_e32 v42, v127
	v_mov_b32_e32 v41, v127
	v_mov_b32_e32 v40, v127
	v_mov_b32_e32 v31, v127
	v_mov_b32_e32 v30, v127
	v_mov_b32_e32 v29, v127
	v_mov_b32_e32 v28, v127
	v_mov_b32_e32 v27, v127
	v_mov_b32_e32 v26, v127
	v_mov_b32_e32 v25, v127
	v_mov_b32_e32 v24, v127
	v_mov_b32_e32 v15, v127
	v_mov_b32_e32 v14, v127
	v_mov_b32_e32 v13, v127
	v_mov_b32_e32 v12, v127
	v_mov_b32_e32 v11, v127
	v_mov_b32_e32 v10, v127
	v_mov_b32_e32 v9, v127
	v_mov_b32_e32 v8, v127
	v_mov_b32_e32 v55, v127
	v_mov_b32_e32 v54, v127
	v_mov_b32_e32 v53, v127
	v_mov_b32_e32 v52, v127
	v_mov_b32_e32 v51, v127
	v_mov_b32_e32 v50, v127
	v_mov_b32_e32 v49, v127
	v_mov_b32_e32 v48, v127
	v_mov_b32_e32 v39, v127
	v_mov_b32_e32 v38, v127
	v_mov_b32_e32 v37, v127
	v_mov_b32_e32 v36, v127
	v_mov_b32_e32 v35, v127
	v_mov_b32_e32 v34, v127
	v_mov_b32_e32 v33, v127
	v_mov_b32_e32 v32, v127
	v_mov_b32_e32 v23, v127
	v_mov_b32_e32 v22, v127
	v_mov_b32_e32 v21, v127
	v_mov_b32_e32 v20, v127
	v_mov_b32_e32 v19, v127
	v_mov_b32_e32 v18, v127
	v_mov_b32_e32 v17, v127
	v_mov_b32_e32 v16, v127
	v_mov_b32_e32 v7, v127
	v_mov_b32_e32 v6, v127
	v_mov_b32_e32 v5, v127
	v_mov_b32_e32 v4, v127
	v_mov_b32_e32 v3, v127
	v_mov_b32_e32 v2, v127
	s_waitcnt lgkmcnt(0)
	v_mov_b32_e32 v1, v127
	v_mov_b32_e32 v0, v127
	s_cbranch_vccnz .LBB0_1066
	s_and_b64 s[18:19], s[4:5], exec
	s_cselect_b32 s11, s41, s53
	s_cselect_b32 s39, s40, s52
	s_cselect_b32 s80, s43, s55
	s_cselect_b32 s81, s42, s54
	s_add_u32 s52, s52, 0x40080
	s_addc_u32 s53, s53, 0
	s_add_u32 s44, s54, 0x100
	v_mov_b32_e32 v0, 0
	s_addc_u32 s45, s55, 0
	s_mov_b32 s46, 0
	v_mov_b32_e32 v1, v0
	v_mov_b32_e32 v2, v0
	v_mov_b32_e32 v3, v0
	v_mov_b32_e32 v4, v0
	v_mov_b32_e32 v5, v0
	v_mov_b32_e32 v6, v0
	v_mov_b32_e32 v7, v0
	v_mov_b32_e32 v16, v0
	v_mov_b32_e32 v17, v0
	v_mov_b32_e32 v18, v0
	v_mov_b32_e32 v19, v0
	v_mov_b32_e32 v20, v0
	v_mov_b32_e32 v21, v0
	v_mov_b32_e32 v22, v0
	v_mov_b32_e32 v23, v0
	v_mov_b32_e32 v32, v0
	v_mov_b32_e32 v33, v0
	v_mov_b32_e32 v34, v0
	v_mov_b32_e32 v35, v0
	v_mov_b32_e32 v36, v0
	v_mov_b32_e32 v37, v0
	v_mov_b32_e32 v38, v0
	v_mov_b32_e32 v39, v0
	v_mov_b32_e32 v48, v0
	v_mov_b32_e32 v49, v0
	v_mov_b32_e32 v50, v0
	v_mov_b32_e32 v51, v0
	v_mov_b32_e32 v52, v0
	v_mov_b32_e32 v53, v0
	v_mov_b32_e32 v54, v0
	v_mov_b32_e32 v55, v0
	v_mov_b32_e32 v8, v0
	v_mov_b32_e32 v9, v0
	v_mov_b32_e32 v10, v0
	v_mov_b32_e32 v11, v0
	v_mov_b32_e32 v12, v0
	v_mov_b32_e32 v13, v0
	v_mov_b32_e32 v14, v0
	v_mov_b32_e32 v15, v0
	v_mov_b32_e32 v24, v0
	v_mov_b32_e32 v25, v0
	v_mov_b32_e32 v26, v0
	v_mov_b32_e32 v27, v0
	v_mov_b32_e32 v28, v0
	v_mov_b32_e32 v29, v0
	v_mov_b32_e32 v30, v0
	v_mov_b32_e32 v31, v0
	v_mov_b32_e32 v40, v0
	v_mov_b32_e32 v41, v0
	v_mov_b32_e32 v42, v0
	v_mov_b32_e32 v43, v0
	v_mov_b32_e32 v44, v0
	v_mov_b32_e32 v45, v0
	v_mov_b32_e32 v46, v0
	v_mov_b32_e32 v47, v0
	v_mov_b32_e32 v56, v0
	v_mov_b32_e32 v57, v0
	v_mov_b32_e32 v58, v0
	v_mov_b32_e32 v59, v0
	v_mov_b32_e32 v60, v0
	v_mov_b32_e32 v61, v0
	v_mov_b32_e32 v62, v0
	v_mov_b32_e32 v63, v0
	v_mov_b32_e32 v64, v0
	v_mov_b32_e32 v65, v0
	v_mov_b32_e32 v66, v0
	v_mov_b32_e32 v67, v0
	v_mov_b32_e32 v68, v0
	v_mov_b32_e32 v69, v0
	v_mov_b32_e32 v70, v0
	v_mov_b32_e32 v71, v0
	v_mov_b32_e32 v80, v0
	v_mov_b32_e32 v81, v0
	v_mov_b32_e32 v82, v0
	v_mov_b32_e32 v83, v0
	v_mov_b32_e32 v84, v0
	v_mov_b32_e32 v85, v0
	v_mov_b32_e32 v86, v0
	v_mov_b32_e32 v87, v0
	v_mov_b32_e32 v96, v0
	v_mov_b32_e32 v97, v0
	v_mov_b32_e32 v98, v0
	v_mov_b32_e32 v99, v0
	v_mov_b32_e32 v100, v0
	v_mov_b32_e32 v101, v0
	v_mov_b32_e32 v102, v0
	v_mov_b32_e32 v103, v0
	v_mov_b32_e32 v112, v0
	v_mov_b32_e32 v113, v0
	v_mov_b32_e32 v114, v0
	v_mov_b32_e32 v115, v0
	v_mov_b32_e32 v116, v0
	v_mov_b32_e32 v117, v0
	v_mov_b32_e32 v118, v0
	v_mov_b32_e32 v119, v0
	v_mov_b32_e32 v72, v0
	v_mov_b32_e32 v73, v0
	v_mov_b32_e32 v74, v0
	v_mov_b32_e32 v75, v0
	v_mov_b32_e32 v76, v0
	v_mov_b32_e32 v77, v0
	v_mov_b32_e32 v78, v0
	v_mov_b32_e32 v79, v0
	v_mov_b32_e32 v88, v0
	v_mov_b32_e32 v89, v0
	v_mov_b32_e32 v90, v0
	v_mov_b32_e32 v91, v0
	v_mov_b32_e32 v92, v0
	v_mov_b32_e32 v93, v0
	v_mov_b32_e32 v94, v0
	v_mov_b32_e32 v95, v0
	v_mov_b32_e32 v104, v0
	v_mov_b32_e32 v105, v0
	v_mov_b32_e32 v106, v0
	v_mov_b32_e32 v107, v0
	v_mov_b32_e32 v108, v0
	v_mov_b32_e32 v109, v0
	v_mov_b32_e32 v110, v0
	v_mov_b32_e32 v111, v0
	v_mov_b32_e32 v120, v0
	v_mov_b32_e32 v121, v0
	v_mov_b32_e32 v122, v0
	v_mov_b32_e32 v123, v0
	v_mov_b32_e32 v124, v0
	v_mov_b32_e32 v125, v0
	v_mov_b32_e32 v126, v0
	v_mov_b32_e32 v127, v0
	.p2align 6

;     __device__ bool next(int i, Unit& u) const { int pm, pn; if (!so.next(i, pm, pn)) return false; u.pm = pm; u.pn = pn; u.aoff = (unsigned)pm * BM * lda; u.boff = (unsigned)pn * BM * ldb; return true; }
;     __device__ __forceinline__ bool next(int i, Unit& u) const { int pm, pn; if (!so.next(i, pm, pn)) return false; u.pm = pm; u.pn = pn; u.aoff = (unsigned)pm * BM * lda; u.boff = (unsigned)(pm >> 4) * bstride + (unsigned)pn * BM * ldb; return true; }
;     __device__ __forceinline__ bool next(int i, Unit& u) const { int pm, pn; if (!so.next(i, pm, pn)) return false; u.pm = pm; u.pn = ((pn & 12) == 4 || (pn & 12) == 8) ? (pn ^ 12) : pn; u.aoff = (unsigned)pm * BM * lda; u.boff = (unsigned)pn * BM * ldb; return true; }
; template <class Epi, class Sched, bool ALIGN_EPI>
; __device__ __forceinline__ void gemm_phase(LAS unsigned char* lds, const Gemm g, const Sched& S, const Epi& E) {
;     ...
;         const bool has_next = S.next(ui + 1, nxt);
;         const char* nA = has_next ? (const char*)g.A + (size_t)nxt.aoff * 2 : cA; const char* nB = has_next ? (const char*)g.Bt + (size_t)nxt.boff * 2 : cB;
;     ...
;         for (int a = 0; a < 2; ++a)
; #pragma unroll
;             for (int b = 0; b < 2; ++b)
; #pragma unroll
;                 for (int m = 0; m < 4; ++m)
; #pragma unroll
;                     for (int n = 0; n < 2; ++n) acc[a][b][m][n] = (f32x4){0.f, 0.f, 0.f, 0.f};
.LBB0_1147:
	s_lshl_b64 s[18:19], s[22:23], 1
	s_add_u32 s42, s50, s18
	s_addc_u32 s43, s51, s19
	s_and_b64 s[18:19], s[2:3], exec
	s_mov_b32 s41, s23
	s_cselect_b32 s74, s43, s5
	s_cselect_b32 s75, s42, s4
	s_lshl_b64 s[18:19], s[40:41], 1
	s_add_u32 s52, s8, s18
	s_addc_u32 s53, s9, s19
	s_and_b64 s[18:19], s[2:3], exec
	s_cselect_b32 s41, s53, s7
	s_cselect_b32 s76, s52, s6
	s_add_u32 s4, s4, 0x80080
	s_addc_u32 s5, s5, 0
	s_add_u32 s44, s6, 0x100
	v_mov_b32_e32 v0, 0
	s_addc_u32 s45, s7, 0
	s_mov_b32 s46, -2
	v_mov_b32_e32 v1, v0
	v_mov_b32_e32 v2, v0
	v_mov_b32_e32 v3, v0
	v_mov_b32_e32 v8, v0
	v_mov_b32_e32 v9, v0
	v_mov_b32_e32 v10, v0
	v_mov_b32_e32 v11, v0
	v_mov_b32_e32 v16, v0
	v_mov_b32_e32 v17, v0
	v_mov_b32_e32 v18, v0
	v_mov_b32_e32 v19, v0
	v_mov_b32_e32 v24, v0
	v_mov_b32_e32 v25, v0
	v_mov_b32_e32 v26, v0
	v_mov_b32_e32 v27, v0
	v_mov_b32_e32 v32, v0
	v_mov_b32_e32 v33, v0
	v_mov_b32_e32 v34, v0
	v_mov_b32_e32 v35, v0
	v_mov_b32_e32 v40, v0
	v_mov_b32_e32 v41, v0
	v_mov_b32_e32 v42, v0
	v_mov_b32_e32 v43, v0
	v_mov_b32_e32 v48, v0
	v_mov_b32_e32 v49, v0
	v_mov_b32_e32 v50, v0
	v_mov_b32_e32 v51, v0
	v_mov_b32_e32 v56, v0
	v_mov_b32_e32 v57, v0
	v_mov_b32_e32 v58, v0
	v_mov_b32_e32 v59, v0
	v_mov_b32_e32 v4, v0
	v_mov_b32_e32 v5, v0
	v_mov_b32_e32 v6, v0
	v_mov_b32_e32 v7, v0
	v_mov_b32_e32 v12, v0
	v_mov_b32_e32 v13, v0
	v_mov_b32_e32 v14, v0
	v_mov_b32_e32 v15, v0
	v_mov_b32_e32 v20, v0
	v_mov_b32_e32 v21, v0
	v_mov_b32_e32 v22, v0
	v_mov_b32_e32 v23, v0
	v_mov_b32_e32 v28, v0
	v_mov_b32_e32 v29, v0
	v_mov_b32_e32 v30, v0
	v_mov_b32_e32 v31, v0
	v_mov_b32_e32 v36, v0
	v_mov_b32_e32 v37, v0
	v_mov_b32_e32 v38, v0
	v_mov_b32_e32 v39, v0
	v_mov_b32_e32 v44, v0
	v_mov_b32_e32 v45, v0
	v_mov_b32_e32 v46, v0
	v_mov_b32_e32 v47, v0
	v_mov_b32_e32 v52, v0
	v_mov_b32_e32 v53, v0
	v_mov_b32_e32 v54, v0
	v_mov_b32_e32 v55, v0
	v_mov_b32_e32 v60, v0
	v_mov_b32_e32 v61, v0
	v_mov_b32_e32 v62, v0
	v_mov_b32_e32 v63, v0
	v_mov_b32_e32 v64, v0
	v_mov_b32_e32 v65, v0
	v_mov_b32_e32 v66, v0
	v_mov_b32_e32 v67, v0
	v_mov_b32_e32 v72, v0
	v_mov_b32_e32 v73, v0
	v_mov_b32_e32 v74, v0
	v_mov_b32_e32 v75, v0
	v_mov_b32_e32 v80, v0
	v_mov_b32_e32 v81, v0
	v_mov_b32_e32 v82, v0
	v_mov_b32_e32 v83, v0
	v_mov_b32_e32 v88, v0
	v_mov_b32_e32 v89, v0
	v_mov_b32_e32 v90, v0
	v_mov_b32_e32 v91, v0
	v_mov_b32_e32 v96, v0
	v_mov_b32_e32 v97, v0
	v_mov_b32_e32 v98, v0
	v_mov_b32_e32 v99, v0
	v_mov_b32_e32 v104, v0
	v_mov_b32_e32 v105, v0
	v_mov_b32_e32 v106, v0
	v_mov_b32_e32 v107, v0
	v_mov_b32_e32 v112, v0
	v_mov_b32_e32 v113, v0
	v_mov_b32_e32 v114, v0
	v_mov_b32_e32 v115, v0
	v_mov_b32_e32 v120, v0
	v_mov_b32_e32 v121, v0
	v_mov_b32_e32 v122, v0
	v_mov_b32_e32 v123, v0
	v_mov_b32_e32 v68, v0
	v_mov_b32_e32 v69, v0
	v_mov_b32_e32 v70, v0
	v_mov_b32_e32 v71, v0
	v_mov_b32_e32 v76, v0
	v_mov_b32_e32 v77, v0
	v_mov_b32_e32 v78, v0
	v_mov_b32_e32 v79, v0
	v_mov_b32_e32 v84, v0
	v_mov_b32_e32 v85, v0
	v_mov_b32_e32 v86, v0
	v_mov_b32_e32 v87, v0
	v_mov_b32_e32 v92, v0
	v_mov_b32_e32 v93, v0
	v_mov_b32_e32 v94, v0
	v_mov_b32_e32 v95, v0
	v_mov_b32_e32 v100, v0
	v_mov_b32_e32 v101, v0
	v_mov_b32_e32 v102, v0
	v_mov_b32_e32 v103, v0
	v_mov_b32_e32 v108, v0
	v_mov_b32_e32 v109, v0
	v_mov_b32_e32 v110, v0
	v_mov_b32_e32 v111, v0
	v_mov_b32_e32 v116, v0
	v_mov_b32_e32 v117, v0
	v_mov_b32_e32 v118, v0
	v_mov_b32_e32 v119, v0
	v_mov_b32_e32 v124, v0
	v_mov_b32_e32 v125, v0
	v_mov_b32_e32 v126, v0
	v_mov_b32_e32 v127, v0
	.p2align 6

;     __device__ bool next(int i, Unit& u) const { int pm, pn; if (!so.next(i, pm, pn)) return false; u.pm = pm; u.pn = pn; u.aoff = (unsigned)pm * BM * lda; u.boff = (unsigned)pn * BM * ldb; return true; }
;     __device__ __forceinline__ bool next(int i, Unit& u) const { int pm, pn; if (!so.next(i, pm, pn)) return false; u.pm = pm; u.pn = pn; u.aoff = (unsigned)pm * BM * lda; u.boff = (unsigned)(pm >> 4) * bstride + (unsigned)pn * BM * ldb; return true; }
;     __device__ __forceinline__ bool next(int i, Unit& u) const { int pm, pn; if (!so.next(i, pm, pn)) return false; u.pm = pm; u.pn = ((pn & 12) == 4 || (pn & 12) == 8) ? (pn ^ 12) : pn; u.aoff = (unsigned)pm * BM * lda; u.boff = (unsigned)pn * BM * ldb; return true; }
; template <class Epi, class Sched, bool ALIGN_EPI>
; __device__ __forceinline__ void gemm_phase(LAS unsigned char* lds, const Gemm g, const Sched& S, const Epi& E) {
;     ...
;         const bool has_next = S.next(ui + 1, nxt);
;         const char* nA = has_next ? (const char*)g.A + (size_t)nxt.aoff * 2 : cA; const char* nB = has_next ? (const char*)g.Bt + (size_t)nxt.boff * 2 : cB;
;     ...
;         for (int a = 0; a < 2; ++a)
; #pragma unroll
;             for (int b = 0; b < 2; ++b)
; #pragma unroll
;                 for (int m = 0; m < 4; ++m)
; #pragma unroll
;                     for (int n = 0; n < 2; ++n) acc[a][b][m][n] = (f32x4){0.f, 0.f, 0.f, 0.f};
.LBB0_1233:
	s_lshl_b64 s[18:19], s[6:7], 1
	s_add_u32 s30, s28, s18
	s_addc_u32 s31, s29, s19
	s_and_b64 s[18:19], s[4:5], exec
	s_mov_b32 s27, s7
	s_cselect_b32 s70, s31, s39
	s_cselect_b32 s71, s30, s38
	s_lshl_b64 s[18:19], s[26:27], 1
	s_add_u32 s36, s82, s18
	s_addc_u32 s37, s83, s19
	s_and_b64 s[18:19], s[4:5], exec
	s_cselect_b32 s27, s37, s41
	s_cselect_b32 s72, s36, s40
	s_add_u32 s38, s38, 0x160080
	s_addc_u32 s39, s39, 0
	s_add_u32 s44, s40, 0x100
	v_mov_b32_e32 v0, 0
	s_addc_u32 s45, s41, 0
	s_mov_b32 s46, -2
	s_waitcnt lgkmcnt(0)
	v_mov_b32_e32 v1, v0
	v_mov_b32_e32 v2, v0
	v_mov_b32_e32 v3, v0
	v_mov_b32_e32 v4, v0
	v_mov_b32_e32 v5, v0
	v_mov_b32_e32 v6, v0
	v_mov_b32_e32 v7, v0
	v_mov_b32_e32 v16, v0
	v_mov_b32_e32 v17, v0
	v_mov_b32_e32 v18, v0
	v_mov_b32_e32 v19, v0
	v_mov_b32_e32 v20, v0
	v_mov_b32_e32 v21, v0
	v_mov_b32_e32 v22, v0
	v_mov_b32_e32 v23, v0
	v_mov_b32_e32 v32, v0
	v_mov_b32_e32 v33, v0
	v_mov_b32_e32 v34, v0
	v_mov_b32_e32 v35, v0
	v_mov_b32_e32 v36, v0
	v_mov_b32_e32 v37, v0
	v_mov_b32_e32 v38, v0
	v_mov_b32_e32 v39, v0
	v_mov_b32_e32 v48, v0
	v_mov_b32_e32 v49, v0
	v_mov_b32_e32 v50, v0
	v_mov_b32_e32 v51, v0
	v_mov_b32_e32 v52, v0
	v_mov_b32_e32 v53, v0
	v_mov_b32_e32 v54, v0
	v_mov_b32_e32 v55, v0
	v_mov_b32_e32 v8, v0
	v_mov_b32_e32 v9, v0
	v_mov_b32_e32 v10, v0
	v_mov_b32_e32 v11, v0
	v_mov_b32_e32 v12, v0
	v_mov_b32_e32 v13, v0
	v_mov_b32_e32 v14, v0
	v_mov_b32_e32 v15, v0
	v_mov_b32_e32 v24, v0
	v_mov_b32_e32 v25, v0
	v_mov_b32_e32 v26, v0
	v_mov_b32_e32 v27, v0
	v_mov_b32_e32 v28, v0
	v_mov_b32_e32 v29, v0
	v_mov_b32_e32 v30, v0
	v_mov_b32_e32 v31, v0
	v_mov_b32_e32 v40, v0
	v_mov_b32_e32 v41, v0
	v_mov_b32_e32 v42, v0
	v_mov_b32_e32 v43, v0
	v_mov_b32_e32 v44, v0
	v_mov_b32_e32 v45, v0
	v_mov_b32_e32 v46, v0
	v_mov_b32_e32 v47, v0
	v_mov_b32_e32 v56, v0
	v_mov_b32_e32 v57, v0
	v_mov_b32_e32 v58, v0
	v_mov_b32_e32 v59, v0
	v_mov_b32_e32 v60, v0
	v_mov_b32_e32 v61, v0
	v_mov_b32_e32 v62, v0
	v_mov_b32_e32 v63, v0
	v_mov_b32_e32 v64, v0
	v_mov_b32_e32 v65, v0
	v_mov_b32_e32 v66, v0
	v_mov_b32_e32 v67, v0
	v_mov_b32_e32 v68, v0
	v_mov_b32_e32 v69, v0
	v_mov_b32_e32 v70, v0
	v_mov_b32_e32 v71, v0
	v_mov_b32_e32 v80, v0
	v_mov_b32_e32 v81, v0
	v_mov_b32_e32 v82, v0
	v_mov_b32_e32 v83, v0
	v_mov_b32_e32 v84, v0
	v_mov_b32_e32 v85, v0
	v_mov_b32_e32 v86, v0
	v_mov_b32_e32 v87, v0
	v_mov_b32_e32 v96, v0
	v_mov_b32_e32 v97, v0
	v_mov_b32_e32 v98, v0
	v_mov_b32_e32 v99, v0
	v_mov_b32_e32 v100, v0
	v_mov_b32_e32 v101, v0
	v_mov_b32_e32 v102, v0
	v_mov_b32_e32 v103, v0
	v_mov_b32_e32 v112, v0
	v_mov_b32_e32 v113, v0
	v_mov_b32_e32 v114, v0
	v_mov_b32_e32 v115, v0
	v_mov_b32_e32 v116, v0
	v_mov_b32_e32 v117, v0
	v_mov_b32_e32 v118, v0
	v_mov_b32_e32 v119, v0
	v_mov_b32_e32 v72, v0
	v_mov_b32_e32 v73, v0
	v_mov_b32_e32 v74, v0
	v_mov_b32_e32 v75, v0
	v_mov_b32_e32 v76, v0
	v_mov_b32_e32 v77, v0
	v_mov_b32_e32 v78, v0
	v_mov_b32_e32 v79, v0
	v_mov_b32_e32 v88, v0
	v_mov_b32_e32 v89, v0
	v_mov_b32_e32 v90, v0
	v_mov_b32_e32 v91, v0
	v_mov_b32_e32 v92, v0
	v_mov_b32_e32 v93, v0
	v_mov_b32_e32 v94, v0
	v_mov_b32_e32 v95, v0
	v_mov_b32_e32 v104, v0
	v_mov_b32_e32 v105, v0
	v_mov_b32_e32 v106, v0
	v_mov_b32_e32 v107, v0
	v_mov_b32_e32 v108, v0
	v_mov_b32_e32 v109, v0
	v_mov_b32_e32 v110, v0
	v_mov_b32_e32 v111, v0
	v_mov_b32_e32 v120, v0
	v_mov_b32_e32 v121, v0
	v_mov_b32_e32 v122, v0
	v_mov_b32_e32 v123, v0
	v_mov_b32_e32 v124, v0
	v_mov_b32_e32 v125, v0
	v_mov_b32_e32 v126, v0
	v_mov_b32_e32 v127, v0
	.p2align 6

;     __device__ bool next(int i, Unit& u) const { int pm, pn; if (!so.next(i, pm, pn)) return false; u.pm = pm; u.pn = pn; u.aoff = (unsigned)pm * BM * lda; u.boff = (unsigned)pn * BM * ldb; return true; }
;     __device__ __forceinline__ bool next(int i, Unit& u) const { int pm, pn; if (!so.next(i, pm, pn)) return false; u.pm = pm; u.pn = pn; u.aoff = (unsigned)pm * BM * lda; u.boff = (unsigned)(pm >> 4) * bstride + (unsigned)pn * BM * ldb; return true; }
;     __device__ __forceinline__ bool next(int i, Unit& u) const { int pm, pn; if (!so.next(i, pm, pn)) return false; u.pm = pm; u.pn = ((pn & 12) == 4 || (pn & 12) == 8) ? (pn ^ 12) : pn; u.aoff = (unsigned)pm * BM * lda; u.boff = (unsigned)pn * BM * ldb; return true; }
; template <class Epi, class Sched, bool ALIGN_EPI>
; __device__ __forceinline__ void gemm_phase(LAS unsigned char* lds, const Gemm g, const Sched& S, const Epi& E) {
;     ...
;         const bool has_next = S.next(ui + 1, nxt);
;         const char* nA = has_next ? (const char*)g.A + (size_t)nxt.aoff * 2 : cA; const char* nB = has_next ? (const char*)g.Bt + (size_t)nxt.boff * 2 : cB;
;     ...
;         for (int a = 0; a < 2; ++a)
; #pragma unroll
;             for (int b = 0; b < 2; ++b)
; #pragma unroll
;                 for (int m = 0; m < 4; ++m)
; #pragma unroll
;                     for (int n = 0; n < 2; ++n) acc[a][b][m][n] = (f32x4){0.f, 0.f, 0.f, 0.f};
.LBB0_1277:
	s_mov_b32 s39, s25
	s_lshl_b64 s[18:19], s[38:39], 1
	s_add_u32 s42, s28, s18
	s_addc_u32 s43, s29, s19
	s_and_b64 s[18:19], s[8:9], exec
	s_mov_b32 s41, s25
	s_cselect_b32 s11, s43, s55
	s_cselect_b32 s39, s42, s54
	s_lshl_b64 s[18:19], s[40:41], 1
	s_add_u32 s52, s82, s18
	s_addc_u32 s53, s83, s19
	s_and_b64 s[18:19], s[8:9], exec
	s_cselect_b32 s41, s53, s57
	s_cselect_b32 s78, s52, s56
	s_add_u32 s54, s54, 0x160080
	s_addc_u32 s55, s55, 0
	s_add_u32 s44, s56, 0x100
	v_mov_b32_e32 v0, 0
	s_addc_u32 s45, s57, 0
	s_mov_b32 s46, -2
	v_mov_b32_e32 v1, v0
	v_mov_b32_e32 v2, v0
	v_mov_b32_e32 v3, v0
	v_mov_b32_e32 v4, v0
	v_mov_b32_e32 v5, v0
	v_mov_b32_e32 v6, v0
	v_mov_b32_e32 v7, v0
	v_mov_b32_e32 v16, v0
	v_mov_b32_e32 v17, v0
	v_mov_b32_e32 v18, v0
	v_mov_b32_e32 v19, v0
	v_mov_b32_e32 v20, v0
	v_mov_b32_e32 v21, v0
	v_mov_b32_e32 v22, v0
	v_mov_b32_e32 v23, v0
	v_mov_b32_e32 v32, v0
	v_mov_b32_e32 v33, v0
	v_mov_b32_e32 v34, v0
	v_mov_b32_e32 v35, v0
	v_mov_b32_e32 v36, v0
	v_mov_b32_e32 v37, v0
	v_mov_b32_e32 v38, v0
	v_mov_b32_e32 v39, v0
	v_mov_b32_e32 v48, v0
	v_mov_b32_e32 v49, v0
	v_mov_b32_e32 v50, v0
	v_mov_b32_e32 v51, v0
	v_mov_b32_e32 v52, v0
	v_mov_b32_e32 v53, v0
	v_mov_b32_e32 v54, v0
	v_mov_b32_e32 v55, v0
	v_mov_b32_e32 v8, v0
	v_mov_b32_e32 v9, v0
	v_mov_b32_e32 v10, v0
	v_mov_b32_e32 v11, v0
	v_mov_b32_e32 v12, v0
	v_mov_b32_e32 v13, v0
	v_mov_b32_e32 v14, v0
	v_mov_b32_e32 v15, v0
	v_mov_b32_e32 v24, v0
	v_mov_b32_e32 v25, v0
	v_mov_b32_e32 v26, v0
	v_mov_b32_e32 v27, v0
	v_mov_b32_e32 v28, v0
	v_mov_b32_e32 v29, v0
	v_mov_b32_e32 v30, v0
	v_mov_b32_e32 v31, v0
	v_mov_b32_e32 v40, v0
	v_mov_b32_e32 v41, v0
	v_mov_b32_e32 v42, v0
	v_mov_b32_e32 v43, v0
	v_mov_b32_e32 v44, v0
	v_mov_b32_e32 v45, v0
	v_mov_b32_e32 v46, v0
	v_mov_b32_e32 v47, v0
	v_mov_b32_e32 v56, v0
	v_mov_b32_e32 v57, v0
	v_mov_b32_e32 v58, v0
	v_mov_b32_e32 v59, v0
	v_mov_b32_e32 v60, v0
	v_mov_b32_e32 v61, v0
	v_mov_b32_e32 v62, v0
	v_mov_b32_e32 v63, v0
	v_mov_b32_e32 v64, v0
	v_mov_b32_e32 v65, v0
	v_mov_b32_e32 v66, v0
	v_mov_b32_e32 v67, v0
	v_mov_b32_e32 v68, v0
	v_mov_b32_e32 v69, v0
	v_mov_b32_e32 v70, v0
	v_mov_b32_e32 v71, v0
	v_mov_b32_e32 v80, v0
	v_mov_b32_e32 v81, v0
	v_mov_b32_e32 v82, v0
	v_mov_b32_e32 v83, v0
	v_mov_b32_e32 v84, v0
	v_mov_b32_e32 v85, v0
	v_mov_b32_e32 v86, v0
	v_mov_b32_e32 v87, v0
	v_mov_b32_e32 v96, v0
	v_mov_b32_e32 v97, v0
	v_mov_b32_e32 v98, v0
	v_mov_b32_e32 v99, v0
	v_mov_b32_e32 v100, v0
	v_mov_b32_e32 v101, v0
	v_mov_b32_e32 v102, v0
	v_mov_b32_e32 v103, v0
	v_mov_b32_e32 v112, v0
	v_mov_b32_e32 v113, v0
	v_mov_b32_e32 v114, v0
	v_mov_b32_e32 v115, v0
	v_mov_b32_e32 v116, v0
	v_mov_b32_e32 v117, v0
	v_mov_b32_e32 v118, v0
	v_mov_b32_e32 v119, v0
	v_mov_b32_e32 v72, v0
	v_mov_b32_e32 v73, v0
	v_mov_b32_e32 v74, v0
	v_mov_b32_e32 v75, v0
	v_mov_b32_e32 v76, v0
	v_mov_b32_e32 v77, v0
	v_mov_b32_e32 v78, v0
	v_mov_b32_e32 v79, v0
	v_mov_b32_e32 v88, v0
	v_mov_b32_e32 v89, v0
	v_mov_b32_e32 v90, v0
	v_mov_b32_e32 v91, v0
	v_mov_b32_e32 v92, v0
	v_mov_b32_e32 v93, v0
	v_mov_b32_e32 v94, v0
	v_mov_b32_e32 v95, v0
	v_mov_b32_e32 v104, v0
	v_mov_b32_e32 v105, v0
	v_mov_b32_e32 v106, v0
	v_mov_b32_e32 v107, v0
	v_mov_b32_e32 v108, v0
	v_mov_b32_e32 v109, v0
	v_mov_b32_e32 v110, v0
	v_mov_b32_e32 v111, v0
	v_mov_b32_e32 v120, v0
	v_mov_b32_e32 v121, v0
	v_mov_b32_e32 v122, v0
	v_mov_b32_e32 v123, v0
	v_mov_b32_e32 v124, v0
	v_mov_b32_e32 v125, v0
	v_mov_b32_e32 v126, v0
	v_mov_b32_e32 v127, v0
	.p2align 6
